# static priority (asm guide 7.4): per-phase s_setprio flips deleted in the 4 main GEMM K-loops, one s_setprio 1 per tile for waves 4-7 (younger half), s_setprio 0 after the loop
# speedup vs baseline: 1.0132x; 1.0127x over previous
; #define WAIT_V(n) asm volatile("s_waitcnt vmcnt(" #n ")" ::: "memory")
; #define WAIT_L(n) asm volatile("s_waitcnt lgkmcnt(" #n ")" ::: "memory")
; #define BAR __builtin_amdgcn_s_barrier()
; #define SCHED __builtin_amdgcn_sched_barrier(0)
; #define STG_A(b, h, ptr) do { const char* _g = (ptr) + (h) * ahalf; LAS unsigned char* _l = lw + ((b) * 2 + (h)) * 16384; GLDS(_g + voa0, _l); GLDS(_g + voa1, _l + 8192); } while (0)
; #define STG_B(b, h, ptr) do { const char* _g = (ptr) + (h) * bhalf; LAS unsigned char* _l = lw + 65536 + ((b) * 2 + (h)) * 16384; GLDS(_g + vob0, _l); GLDS(_g + vob1, _l + 8192); } while (0)
; #define LDA(dst, b, h) _Pragma("unroll") for (int m = 0; m < 4; ++m) _Pragma("unroll") for (int k = 0; k < 2; ++k) dst[m][k] = *(const LAS bf16x8*)(la + ((b) * 2 + (h)) * 16384 + m * 2048 + k * 1024)
;     DEV void prefetch(LAS unsigned char* lds, int brow, int par, int tid) const { if (tid < 256) GLDS(ss + (size_t)(brow + tid) * 4, lds + LDS_EX + par * 4096 + tid * 16); }
; template <int BMODE, class Epi, class TileFn>
; DEV void gemm_loop(LAS unsigned char* lds, const bf16_t* __restrict__ A, int lda, const bf16_t* __restrict__ B, int ldb, int K, const Epi& epi, int t0, int tstep, int tend, const TileFn& tf) {
;     ...
;     int par = 0;
;     for (int tt = t0;; tt += tstep, par ^= 1) {
;         const bool has_next = tt + tstep < tend;
;         epi.prefetch(lds, brow, par, tid);
;         int nrow = brow, ncol = bcol;
;         if (has_next) tf(tt + tstep, nrow, ncol);
;         const char* nA = (const char*)(A + (size_t)nrow * lda);
;         const char* nB = BMODE == 0 ? (const char*)(B + (size_t)ncol * ldb) : (const char*)(B + (size_t)ncol * 8);
;         for (int t = 0; t < nt; t += 2) {
;             const bool last = (t == nt - 2);
;             const char* a1 = cA + (size_t)(t + 1) * 128;
;             const char* a2 = last ? nA : cA + (size_t)(t + 2) * 128;
;             const char* b2 = last ? nB : cB + (size_t)(t + 2) * bks;
;             const char* a3 = a2 + 128; const char* b3 = b2 + bks;
;             LDB(B0, 0, 0); LDB(B1, 0, 1); SCHED; LDA(At, 0, 0); STG_A(1, 1, a1);
;             WAIT_V(8); WAIT_L(0); BAR; MMA(0, 0, At, B0); MMA(0, 1, At, B1); BAR; SCHED;
;             LDA(At, 0, 1); STG_B(0, 0, b2); STG_B(0, 1, b2); STG_A(0, 0, a2);
;             WAIT_V(8); WAIT_L(0); BAR; MMA(1, 0, At, B0); MMA(1, 1, At, B1); BAR; SCHED;
.LBB0_440:
	s_ashr_i32 s53, s52, 31
	s_lshl_b64 s[76:77], s[52:53], 11
	s_add_u32 s29, s72, s76
	s_addc_u32 s30, s73, s77
	s_ashr_i32 s55, s54, 31
	s_lshl_b64 s[80:81], s[54:55], 11
	s_add_u32 s50, s46, s80
	s_addc_u32 s53, s47, s81
	s_add_u32 s55, s66, s36
	s_addc_u32 s74, s67, s37
	v_readlane_b32 s31, v254, 51
	s_add_u32 s75, s31, s8
	v_readlane_b32 s8, v254, 52
	v_lshl_add_u64 v[140:141], v[136:137], 0, s[36:37]
	v_lshl_add_u64 v[142:143], v[138:139], 0, s[36:37]
	s_addc_u32 s83, s8, s9
	s_mov_b32 s92, -2
	s_mov_b64 s[36:37], 0
	v_readfirstlane_b32 s100, v188
	s_nop 3
	s_cmp_lt_u32 s100, 0x100
	s_cbranch_scc1 .Lsp_441
	s_setprio 1
.Lsp_441:
	ds_read_b128 v[162:165], v160
	ds_read_b128 v[166:169], v160 offset:1024
	ds_read_b128 v[170:173], v160 offset:2048
	ds_read_b128 v[174:177], v160 offset:3072
	ds_read_b128 v[178:181], v160 offset:16384
	ds_read_b128 v[182:185], v160 offset:17408
	ds_read_b128 v[196:199], v160 offset:18432
	ds_read_b128 v[200:203], v160 offset:19456
	s_add_u32 s8, s55, s36
	s_addc_u32 s9, s74, s37
	s_add_u32 s8, s8, 0x62e6100
	s_addc_u32 s9, s9, 0
	s_add_u32 s31, s75, s36
	s_addc_u32 s93, s83, s37
	s_cmpk_eq_i32 s36, 0x700
	s_cselect_b32 s45, s30, s9
	s_cselect_b32 s44, s29, s8
	s_cselect_b32 s9, s53, s93
	s_cselect_b32 s8, s50, s31
	v_add_u32_e32 v194, 0xc000, v145
	v_lshl_add_u64 v[186:187], v[140:141], 0, s[36:37]
	v_readfirstlane_b32 s31, v194
	v_add_u32_e32 v194, 0xe000, v145
	s_mov_b32 m0, s31
	v_readfirstlane_b32 s31, v194
	ds_read_b128 v[212:215], v161
	ds_read_b128 v[216:219], v161 offset:1024
	ds_read_b128 v[220:223], v161 offset:2048
	ds_read_b128 v[224:227], v161 offset:3072
	ds_read_b128 v[228:231], v161 offset:4096
	ds_read_b128 v[232:235], v161 offset:5120
	ds_read_b128 v[236:239], v161 offset:6144
	ds_read_b128 v[240:243], v161 offset:7168
	global_load_lds_dwordx4 v[186:187], off
	v_lshl_add_u64 v[186:187], v[142:143], 0, s[36:37]
	s_mov_b32 m0, s31
	s_nop 0
	global_load_lds_dwordx4 v[186:187], off
	s_waitcnt vmcnt(8)
	s_waitcnt lgkmcnt(0)
	s_barrier
	s_waitcnt lgkmcnt(0)
	v_mfma_f32_16x16x32_bf16 v[124:127], v[162:165], v[212:215], 0
	v_mfma_f32_16x16x32_bf16 v[120:123], v[170:173], v[212:215], 0
	v_mfma_f32_16x16x32_bf16 v[108:111], v[162:165], v[220:223], 0
	v_mfma_f32_16x16x32_bf16 v[104:107], v[170:173], v[220:223], 0
	v_mfma_f32_16x16x32_bf16 v[92:95], v[162:165], v[228:231], 0
	v_mfma_f32_16x16x32_bf16 v[88:91], v[170:173], v[228:231], 0
	v_mfma_f32_16x16x32_bf16 v[76:79], v[162:165], v[236:239], 0
	v_mfma_f32_16x16x32_bf16 v[72:75], v[170:173], v[236:239], 0
	v_mfma_f32_16x16x32_bf16 v[124:127], v[166:169], v[216:219], v[124:127]
	v_mfma_f32_16x16x32_bf16 v[120:123], v[174:177], v[216:219], v[120:123]
	v_mfma_f32_16x16x32_bf16 v[108:111], v[166:169], v[224:227], v[108:111]
	v_mfma_f32_16x16x32_bf16 v[104:107], v[174:177], v[224:227], v[104:107]
	v_mfma_f32_16x16x32_bf16 v[92:95], v[166:169], v[232:235], v[92:95]
	v_mfma_f32_16x16x32_bf16 v[88:91], v[174:177], v[232:235], v[88:91]
	v_mfma_f32_16x16x32_bf16 v[76:79], v[166:169], v[240:243], v[76:79]
	v_mfma_f32_16x16x32_bf16 v[72:75], v[174:177], v[240:243], v[72:75]
	v_mfma_f32_16x16x32_bf16 v[116:119], v[178:181], v[212:215], 0
	v_mfma_f32_16x16x32_bf16 v[112:115], v[196:199], v[212:215], 0
	v_mfma_f32_16x16x32_bf16 v[100:103], v[178:181], v[220:223], 0
	v_mfma_f32_16x16x32_bf16 v[96:99], v[196:199], v[220:223], 0
	v_mfma_f32_16x16x32_bf16 v[84:87], v[178:181], v[228:231], 0
	v_mfma_f32_16x16x32_bf16 v[80:83], v[196:199], v[228:231], 0
	v_mfma_f32_16x16x32_bf16 v[68:71], v[178:181], v[236:239], 0
	v_mfma_f32_16x16x32_bf16 v[64:67], v[196:199], v[236:239], 0
	v_mfma_f32_16x16x32_bf16 v[116:119], v[182:185], v[216:219], v[116:119]
	v_mfma_f32_16x16x32_bf16 v[112:115], v[200:203], v[216:219], v[112:115]
	v_mfma_f32_16x16x32_bf16 v[100:103], v[182:185], v[224:227], v[100:103]
	v_mfma_f32_16x16x32_bf16 v[96:99], v[200:203], v[224:227], v[96:99]
	v_mfma_f32_16x16x32_bf16 v[84:87], v[182:185], v[232:235], v[84:87]
	v_mfma_f32_16x16x32_bf16 v[80:83], v[200:203], v[232:235], v[80:83]
	v_mfma_f32_16x16x32_bf16 v[68:71], v[182:185], v[240:243], v[68:71]
	v_mfma_f32_16x16x32_bf16 v[64:67], v[200:203], v[240:243], v[64:67]
	s_barrier
	v_readfirstlane_b32 s31, v146
	v_lshl_add_u64 v[186:187], s[8:9], 0, v[130:131]
	s_mov_b32 m0, s31
	v_readfirstlane_b32 s31, v147
	s_add_u32 s94, s8, 0x40000
	ds_read_b128 v[212:215], v161 offset:16384
	ds_read_b128 v[216:219], v161 offset:17408
	ds_read_b128 v[220:223], v161 offset:18432
	ds_read_b128 v[224:227], v161 offset:19456
	ds_read_b128 v[228:231], v161 offset:20480
	ds_read_b128 v[232:235], v161 offset:21504
	ds_read_b128 v[236:239], v161 offset:22528
	ds_read_b128 v[240:243], v161 offset:23552
	global_load_lds_dwordx4 v[186:187], off
	v_lshl_add_u64 v[204:205], s[8:9], 0, v[132:133]
	s_mov_b32 m0, s31
	s_addc_u32 s95, s9, 0
	v_readfirstlane_b32 s31, v148
	global_load_lds_dwordx4 v[204:205], off
	v_lshl_add_u64 v[244:245], s[94:95], 0, v[130:131]
	s_mov_b32 m0, s31
	v_readfirstlane_b32 s31, v149
	global_load_lds_dwordx4 v[244:245], off
	v_lshl_add_u64 v[244:245], s[94:95], 0, v[132:133]
	s_mov_b32 m0, s31
	v_readfirstlane_b32 s31, v145
	global_load_lds_dwordx4 v[244:245], off
	v_lshl_add_u64 v[244:245], s[44:45], 0, v[128:129]
	s_mov_b32 m0, s31
	v_readfirstlane_b32 s31, v150
	global_load_lds_dwordx4 v[244:245], off
	v_lshl_add_u64 v[246:247], s[44:45], 0, v[134:135]
	s_mov_b32 m0, s31
	s_nop 0
	global_load_lds_dwordx4 v[246:247], off
	s_waitcnt vmcnt(8)
	s_waitcnt lgkmcnt(0)
	s_barrier
; #define WAIT_V(n) asm volatile("s_waitcnt vmcnt(" #n ")" ::: "memory")
; #define WAIT_L(n) asm volatile("s_waitcnt lgkmcnt(" #n ")" ::: "memory")
; #define BAR __builtin_amdgcn_s_barrier()
; #define SCHED __builtin_amdgcn_sched_barrier(0)
; #define STG_A(b, h, ptr) do { const char* _g = (ptr) + (h) * ahalf; LAS unsigned char* _l = lw + ((b) * 2 + (h)) * 16384; GLDS(_g + voa0, _l); GLDS(_g + voa1, _l + 8192); } while (0)
; #define STG_B(b, h, ptr) do { const char* _g = (ptr) + (h) * bhalf; LAS unsigned char* _l = lw + 65536 + ((b) * 2 + (h)) * 16384; GLDS(_g + vob0, _l); GLDS(_g + vob1, _l + 8192); } while (0)
; #define LDA(dst, b, h) _Pragma("unroll") for (int m = 0; m < 4; ++m) _Pragma("unroll") for (int k = 0; k < 2; ++k) dst[m][k] = *(const LAS bf16x8*)(la + ((b) * 2 + (h)) * 16384 + m * 2048 + k * 1024)
; #define LDB(dst, b, h) _Pragma("unroll") for (int n = 0; n < 2; ++n) _Pragma("unroll") for (int k = 0; k < 2; ++k) dst[n][k] = *(const LAS bf16x8*)(lb + ((b) * 2 + (h)) * 16384 + n * 2048 + k * 1024)
; #define MMA(ai, bj, Af, Bf) do { __builtin_amdgcn_s_setprio(1); \
;     _Pragma("unroll") for (int m = 0; m < 4; ++m) _Pragma("unroll") for (int n = 0; n < 2; ++n) _Pragma("unroll") for (int k = 0; k < 2; ++k) \
;         acc[ai][bj][m][n] = __builtin_amdgcn_mfma_f32_16x16x32_bf16(Bf[n][k], Af[m][k], acc[ai][bj][m][n], 0, 0, 0); \
;     __builtin_amdgcn_s_setprio(0); } while (0)
; template <int BMODE, class Epi, class TileFn>
; DEV void gemm_loop(LAS unsigned char* lds, const bf16_t* __restrict__ A, int lda, const bf16_t* __restrict__ B, int ldb, int K, const Epi& epi, int t0, int tstep, int tend, const TileFn& tf) {
;     ...
;             LDB(B0, 0, 0); LDB(B1, 0, 1); SCHED; LDA(At, 0, 0); STG_A(1, 1, a1);
;             WAIT_V(8); WAIT_L(0); BAR; MMA(0, 0, At, B0); MMA(0, 1, At, B1); BAR; SCHED;
;             LDA(At, 0, 1); STG_B(0, 0, b2); STG_B(0, 1, b2); STG_A(0, 0, a2);
;             WAIT_V(8); WAIT_L(0); BAR; MMA(1, 0, At, B0); MMA(1, 1, At, B1); BAR; SCHED;
	s_waitcnt lgkmcnt(0)
	v_mfma_f32_16x16x32_bf16 v[60:63], v[162:165], v[212:215], 0
	v_mfma_f32_16x16x32_bf16 v[56:59], v[170:173], v[212:215], 0
	v_mfma_f32_16x16x32_bf16 v[44:47], v[162:165], v[220:223], 0
	v_mfma_f32_16x16x32_bf16 v[40:43], v[170:173], v[220:223], 0
	v_mfma_f32_16x16x32_bf16 v[28:31], v[162:165], v[228:231], 0
	v_mfma_f32_16x16x32_bf16 v[24:27], v[170:173], v[228:231], 0
	v_mfma_f32_16x16x32_bf16 v[12:15], v[162:165], v[236:239], 0
	v_mfma_f32_16x16x32_bf16 v[8:11], v[170:173], v[236:239], 0
	v_mfma_f32_16x16x32_bf16 v[60:63], v[166:169], v[216:219], v[60:63]
	v_mfma_f32_16x16x32_bf16 v[56:59], v[174:177], v[216:219], v[56:59]
	v_mfma_f32_16x16x32_bf16 v[44:47], v[166:169], v[224:227], v[44:47]
	v_mfma_f32_16x16x32_bf16 v[40:43], v[174:177], v[224:227], v[40:43]
	v_mfma_f32_16x16x32_bf16 v[28:31], v[166:169], v[232:235], v[28:31]
	v_mfma_f32_16x16x32_bf16 v[24:27], v[174:177], v[232:235], v[24:27]
	v_mfma_f32_16x16x32_bf16 v[12:15], v[166:169], v[240:243], v[12:15]
	v_mfma_f32_16x16x32_bf16 v[8:11], v[174:177], v[240:243], v[8:11]
	v_mfma_f32_16x16x32_bf16 v[52:55], v[178:181], v[212:215], 0
	v_mfma_f32_16x16x32_bf16 v[48:51], v[196:199], v[212:215], 0
	v_mfma_f32_16x16x32_bf16 v[36:39], v[178:181], v[220:223], 0
	v_mfma_f32_16x16x32_bf16 v[32:35], v[196:199], v[220:223], 0
	v_mfma_f32_16x16x32_bf16 v[20:23], v[178:181], v[228:231], 0
	v_mfma_f32_16x16x32_bf16 v[16:19], v[196:199], v[228:231], 0
	v_mfma_f32_16x16x32_bf16 v[4:7], v[178:181], v[236:239], 0
	v_mfma_f32_16x16x32_bf16 v[0:3], v[196:199], v[236:239], 0
	v_mfma_f32_16x16x32_bf16 v[52:55], v[182:185], v[216:219], v[52:55]
	v_mfma_f32_16x16x32_bf16 v[48:51], v[200:203], v[216:219], v[48:51]
	v_mfma_f32_16x16x32_bf16 v[36:39], v[182:185], v[224:227], v[36:39]
	v_mfma_f32_16x16x32_bf16 v[32:35], v[200:203], v[224:227], v[32:35]
	v_mfma_f32_16x16x32_bf16 v[20:23], v[182:185], v[232:235], v[20:23]
	v_mfma_f32_16x16x32_bf16 v[16:19], v[200:203], v[232:235], v[16:19]
	v_mfma_f32_16x16x32_bf16 v[4:7], v[182:185], v[240:243], v[4:7]
	v_mfma_f32_16x16x32_bf16 v[0:3], v[200:203], v[240:243], v[0:3]
	s_barrier
	s_branch .Lkmid_441
.LBB0_441:
	ds_read_b128 v[162:165], v160
	ds_read_b128 v[166:169], v160 offset:1024
	ds_read_b128 v[170:173], v160 offset:2048
	ds_read_b128 v[174:177], v160 offset:3072
	ds_read_b128 v[178:181], v160 offset:16384
	ds_read_b128 v[182:185], v160 offset:17408
	ds_read_b128 v[196:199], v160 offset:18432
	ds_read_b128 v[200:203], v160 offset:19456
	s_add_u32 s8, s55, s36
	s_addc_u32 s9, s74, s37
	s_add_u32 s8, s8, 0x62e6100
	s_addc_u32 s9, s9, 0
	s_add_u32 s31, s75, s36
	s_addc_u32 s93, s83, s37
	s_cmpk_eq_i32 s36, 0x700
	s_cselect_b32 s45, s30, s9
	s_cselect_b32 s44, s29, s8
	s_cselect_b32 s9, s53, s93
	s_cselect_b32 s8, s50, s31
	v_add_u32_e32 v194, 0xc000, v145
	v_lshl_add_u64 v[186:187], v[140:141], 0, s[36:37]
	v_readfirstlane_b32 s31, v194
	v_add_u32_e32 v194, 0xe000, v145
	s_mov_b32 m0, s31
	v_readfirstlane_b32 s31, v194
	ds_read_b128 v[212:215], v161
	ds_read_b128 v[216:219], v161 offset:1024
	ds_read_b128 v[220:223], v161 offset:2048
	ds_read_b128 v[224:227], v161 offset:3072
	ds_read_b128 v[228:231], v161 offset:4096
	ds_read_b128 v[232:235], v161 offset:5120
	ds_read_b128 v[236:239], v161 offset:6144
	ds_read_b128 v[240:243], v161 offset:7168
	global_load_lds_dwordx4 v[186:187], off
	v_lshl_add_u64 v[186:187], v[142:143], 0, s[36:37]
	s_mov_b32 m0, s31
	s_nop 0
	global_load_lds_dwordx4 v[186:187], off
	s_waitcnt vmcnt(8)
	s_waitcnt lgkmcnt(0)
	s_barrier
	s_waitcnt lgkmcnt(0)
	v_mfma_f32_16x16x32_bf16 v[124:127], v[162:165], v[212:215], v[124:127]
	v_mfma_f32_16x16x32_bf16 v[120:123], v[170:173], v[212:215], v[120:123]
	v_mfma_f32_16x16x32_bf16 v[108:111], v[162:165], v[220:223], v[108:111]
	v_mfma_f32_16x16x32_bf16 v[104:107], v[170:173], v[220:223], v[104:107]
	v_mfma_f32_16x16x32_bf16 v[92:95], v[162:165], v[228:231], v[92:95]
	v_mfma_f32_16x16x32_bf16 v[88:91], v[170:173], v[228:231], v[88:91]
	v_mfma_f32_16x16x32_bf16 v[76:79], v[162:165], v[236:239], v[76:79]
	v_mfma_f32_16x16x32_bf16 v[72:75], v[170:173], v[236:239], v[72:75]
	v_mfma_f32_16x16x32_bf16 v[124:127], v[166:169], v[216:219], v[124:127]
	v_mfma_f32_16x16x32_bf16 v[120:123], v[174:177], v[216:219], v[120:123]
	v_mfma_f32_16x16x32_bf16 v[108:111], v[166:169], v[224:227], v[108:111]
	v_mfma_f32_16x16x32_bf16 v[104:107], v[174:177], v[224:227], v[104:107]
	v_mfma_f32_16x16x32_bf16 v[92:95], v[166:169], v[232:235], v[92:95]
	v_mfma_f32_16x16x32_bf16 v[88:91], v[174:177], v[232:235], v[88:91]
	v_mfma_f32_16x16x32_bf16 v[76:79], v[166:169], v[240:243], v[76:79]
	v_mfma_f32_16x16x32_bf16 v[72:75], v[174:177], v[240:243], v[72:75]
	v_mfma_f32_16x16x32_bf16 v[116:119], v[178:181], v[212:215], v[116:119]
	v_mfma_f32_16x16x32_bf16 v[112:115], v[196:199], v[212:215], v[112:115]
	v_mfma_f32_16x16x32_bf16 v[100:103], v[178:181], v[220:223], v[100:103]
	v_mfma_f32_16x16x32_bf16 v[96:99], v[196:199], v[220:223], v[96:99]
	v_mfma_f32_16x16x32_bf16 v[84:87], v[178:181], v[228:231], v[84:87]
	v_mfma_f32_16x16x32_bf16 v[80:83], v[196:199], v[228:231], v[80:83]
	v_mfma_f32_16x16x32_bf16 v[68:71], v[178:181], v[236:239], v[68:71]
	v_mfma_f32_16x16x32_bf16 v[64:67], v[196:199], v[236:239], v[64:67]
	v_mfma_f32_16x16x32_bf16 v[116:119], v[182:185], v[216:219], v[116:119]
	v_mfma_f32_16x16x32_bf16 v[112:115], v[200:203], v[216:219], v[112:115]
	v_mfma_f32_16x16x32_bf16 v[100:103], v[182:185], v[224:227], v[100:103]
	v_mfma_f32_16x16x32_bf16 v[96:99], v[200:203], v[224:227], v[96:99]
	v_mfma_f32_16x16x32_bf16 v[84:87], v[182:185], v[232:235], v[84:87]
	v_mfma_f32_16x16x32_bf16 v[80:83], v[200:203], v[232:235], v[80:83]
	v_mfma_f32_16x16x32_bf16 v[68:71], v[182:185], v[240:243], v[68:71]
	v_mfma_f32_16x16x32_bf16 v[64:67], v[200:203], v[240:243], v[64:67]
	s_barrier
; #define WAIT_V(n) asm volatile("s_waitcnt vmcnt(" #n ")" ::: "memory")
; #define WAIT_L(n) asm volatile("s_waitcnt lgkmcnt(" #n ")" ::: "memory")
; #define BAR __builtin_amdgcn_s_barrier()
; #define SCHED __builtin_amdgcn_sched_barrier(0)
; #define STG_A(b, h, ptr) do { const char* _g = (ptr) + (h) * ahalf; LAS unsigned char* _l = lw + ((b) * 2 + (h)) * 16384; GLDS(_g + voa0, _l); GLDS(_g + voa1, _l + 8192); } while (0)
; #define STG_B(b, h, ptr) do { const char* _g = (ptr) + (h) * bhalf; LAS unsigned char* _l = lw + 65536 + ((b) * 2 + (h)) * 16384; GLDS(_g + vob0, _l); GLDS(_g + vob1, _l + 8192); } while (0)
; #define LDA(dst, b, h) _Pragma("unroll") for (int m = 0; m < 4; ++m) _Pragma("unroll") for (int k = 0; k < 2; ++k) dst[m][k] = *(const LAS bf16x8*)(la + ((b) * 2 + (h)) * 16384 + m * 2048 + k * 1024)
; #define LDB(dst, b, h) _Pragma("unroll") for (int n = 0; n < 2; ++n) _Pragma("unroll") for (int k = 0; k < 2; ++k) dst[n][k] = *(const LAS bf16x8*)(lb + ((b) * 2 + (h)) * 16384 + n * 2048 + k * 1024)
; #define MMA(ai, bj, Af, Bf) do { __builtin_amdgcn_s_setprio(1); \
;     _Pragma("unroll") for (int m = 0; m < 4; ++m) _Pragma("unroll") for (int n = 0; n < 2; ++n) _Pragma("unroll") for (int k = 0; k < 2; ++k) \
;         acc[ai][bj][m][n] = __builtin_amdgcn_mfma_f32_16x16x32_bf16(Bf[n][k], Af[m][k], acc[ai][bj][m][n], 0, 0, 0); \
;     __builtin_amdgcn_s_setprio(0); } while (0)
; template <int BMODE, class Epi, class TileFn>
; DEV void gemm_loop(LAS unsigned char* lds, const bf16_t* __restrict__ A, int lda, const bf16_t* __restrict__ B, int ldb, int K, const Epi& epi, int t0, int tstep, int tend, const TileFn& tf) {
;     ...
;             LDA(At, 0, 1); STG_B(0, 0, b2); STG_B(0, 1, b2); STG_A(0, 0, a2);
;             WAIT_V(8); WAIT_L(0); BAR; MMA(1, 0, At, B0); MMA(1, 1, At, B1); BAR; SCHED;
;             LDB(B0, 1, 0); LDB(B1, 1, 1); SCHED; LDA(At, 1, 0); STG_A(0, 1, a2);
;             WAIT_V(8); WAIT_L(0); BAR; MMA(0, 0, At, B0); MMA(0, 1, At, B1); BAR; SCHED;
	v_readfirstlane_b32 s31, v146
	v_lshl_add_u64 v[186:187], s[8:9], 0, v[130:131]
	s_mov_b32 m0, s31
	v_readfirstlane_b32 s31, v147
	s_add_u32 s94, s8, 0x40000
	ds_read_b128 v[212:215], v161 offset:16384
	ds_read_b128 v[216:219], v161 offset:17408
	ds_read_b128 v[220:223], v161 offset:18432
	ds_read_b128 v[224:227], v161 offset:19456
	ds_read_b128 v[228:231], v161 offset:20480
	ds_read_b128 v[232:235], v161 offset:21504
	ds_read_b128 v[236:239], v161 offset:22528
	ds_read_b128 v[240:243], v161 offset:23552
	global_load_lds_dwordx4 v[186:187], off
	v_lshl_add_u64 v[204:205], s[8:9], 0, v[132:133]
	s_mov_b32 m0, s31
	s_addc_u32 s95, s9, 0
	v_readfirstlane_b32 s31, v148
	global_load_lds_dwordx4 v[204:205], off
	v_lshl_add_u64 v[244:245], s[94:95], 0, v[130:131]
	s_mov_b32 m0, s31
	v_readfirstlane_b32 s31, v149
	global_load_lds_dwordx4 v[244:245], off
	v_lshl_add_u64 v[244:245], s[94:95], 0, v[132:133]
	s_mov_b32 m0, s31
	v_readfirstlane_b32 s31, v145
	global_load_lds_dwordx4 v[244:245], off
	v_lshl_add_u64 v[244:245], s[44:45], 0, v[128:129]
	s_mov_b32 m0, s31
	v_readfirstlane_b32 s31, v150
	global_load_lds_dwordx4 v[244:245], off
	v_lshl_add_u64 v[246:247], s[44:45], 0, v[134:135]
	s_mov_b32 m0, s31
	s_nop 0
	global_load_lds_dwordx4 v[246:247], off
	s_waitcnt vmcnt(8)
	s_waitcnt lgkmcnt(0)
	s_barrier
	s_waitcnt lgkmcnt(0)
	v_mfma_f32_16x16x32_bf16 v[60:63], v[162:165], v[212:215], v[60:63]
	v_mfma_f32_16x16x32_bf16 v[56:59], v[170:173], v[212:215], v[56:59]
	v_mfma_f32_16x16x32_bf16 v[44:47], v[162:165], v[220:223], v[44:47]
	v_mfma_f32_16x16x32_bf16 v[40:43], v[170:173], v[220:223], v[40:43]
	v_mfma_f32_16x16x32_bf16 v[28:31], v[162:165], v[228:231], v[28:31]
	v_mfma_f32_16x16x32_bf16 v[24:27], v[170:173], v[228:231], v[24:27]
	v_mfma_f32_16x16x32_bf16 v[12:15], v[162:165], v[236:239], v[12:15]
	v_mfma_f32_16x16x32_bf16 v[8:11], v[170:173], v[236:239], v[8:11]
	v_mfma_f32_16x16x32_bf16 v[60:63], v[166:169], v[216:219], v[60:63]
	v_mfma_f32_16x16x32_bf16 v[56:59], v[174:177], v[216:219], v[56:59]
	v_mfma_f32_16x16x32_bf16 v[44:47], v[166:169], v[224:227], v[44:47]
	v_mfma_f32_16x16x32_bf16 v[40:43], v[174:177], v[224:227], v[40:43]
	v_mfma_f32_16x16x32_bf16 v[28:31], v[166:169], v[232:235], v[28:31]
	v_mfma_f32_16x16x32_bf16 v[24:27], v[174:177], v[232:235], v[24:27]
	v_mfma_f32_16x16x32_bf16 v[12:15], v[166:169], v[240:243], v[12:15]
	v_mfma_f32_16x16x32_bf16 v[8:11], v[174:177], v[240:243], v[8:11]
	v_mfma_f32_16x16x32_bf16 v[52:55], v[178:181], v[212:215], v[52:55]
	v_mfma_f32_16x16x32_bf16 v[48:51], v[196:199], v[212:215], v[48:51]
	v_mfma_f32_16x16x32_bf16 v[36:39], v[178:181], v[220:223], v[36:39]
	v_mfma_f32_16x16x32_bf16 v[32:35], v[196:199], v[220:223], v[32:35]
	v_mfma_f32_16x16x32_bf16 v[20:23], v[178:181], v[228:231], v[20:23]
	v_mfma_f32_16x16x32_bf16 v[16:19], v[196:199], v[228:231], v[16:19]
	v_mfma_f32_16x16x32_bf16 v[4:7], v[178:181], v[236:239], v[4:7]
	v_mfma_f32_16x16x32_bf16 v[0:3], v[196:199], v[236:239], v[0:3]
	v_mfma_f32_16x16x32_bf16 v[52:55], v[182:185], v[216:219], v[52:55]
	v_mfma_f32_16x16x32_bf16 v[48:51], v[200:203], v[216:219], v[48:51]
	v_mfma_f32_16x16x32_bf16 v[36:39], v[182:185], v[224:227], v[36:39]
	v_mfma_f32_16x16x32_bf16 v[32:35], v[200:203], v[224:227], v[32:35]
	v_mfma_f32_16x16x32_bf16 v[20:23], v[182:185], v[232:235], v[20:23]
	v_mfma_f32_16x16x32_bf16 v[16:19], v[200:203], v[232:235], v[16:19]
	v_mfma_f32_16x16x32_bf16 v[4:7], v[182:185], v[240:243], v[4:7]
	v_mfma_f32_16x16x32_bf16 v[0:3], v[200:203], v[240:243], v[0:3]
	s_barrier
.Lkmid_441:
	ds_read_b128 v[162:165], v160 offset:32768
	ds_read_b128 v[166:169], v160 offset:33792
	ds_read_b128 v[170:173], v160 offset:34816
	ds_read_b128 v[174:177], v160 offset:35840
	ds_read_b128 v[178:181], v160 offset:49152
	ds_read_b128 v[182:185], v160 offset:50176
	ds_read_b128 v[196:199], v160 offset:51200
	ds_read_b128 v[200:203], v160 offset:52224
	s_add_u32 s44, s44, 0x40000
	s_addc_u32 s45, s45, 0
	v_readfirstlane_b32 s31, v151
	v_lshl_add_u64 v[248:249], s[44:45], 0, v[128:129]
	s_mov_b32 m0, s31
	v_readfirstlane_b32 s31, v152
	ds_read_b128 v[212:215], v161 offset:32768
	ds_read_b128 v[216:219], v161 offset:33792
	ds_read_b128 v[220:223], v161 offset:34816
	ds_read_b128 v[224:227], v161 offset:35840
	ds_read_b128 v[228:231], v161 offset:36864
	ds_read_b128 v[232:235], v161 offset:37888
	ds_read_b128 v[236:239], v161 offset:38912
	ds_read_b128 v[240:243], v161 offset:39936
	global_load_lds_dwordx4 v[248:249], off
	v_lshl_add_u64 v[248:249], s[44:45], 0, v[134:135]
	s_mov_b32 m0, s31
	s_nop 0
	global_load_lds_dwordx4 v[248:249], off
	s_waitcnt vmcnt(8)
	s_waitcnt lgkmcnt(0)
	s_barrier
; #define WAIT_V(n) asm volatile("s_waitcnt vmcnt(" #n ")" ::: "memory")
; #define WAIT_L(n) asm volatile("s_waitcnt lgkmcnt(" #n ")" ::: "memory")
; #define BAR __builtin_amdgcn_s_barrier()
; #define SCHED __builtin_amdgcn_sched_barrier(0)
; #define STG_A(b, h, ptr) do { const char* _g = (ptr) + (h) * ahalf; LAS unsigned char* _l = lw + ((b) * 2 + (h)) * 16384; GLDS(_g + voa0, _l); GLDS(_g + voa1, _l + 8192); } while (0)
; #define STG_B(b, h, ptr) do { const char* _g = (ptr) + (h) * bhalf; LAS unsigned char* _l = lw + 65536 + ((b) * 2 + (h)) * 16384; GLDS(_g + vob0, _l); GLDS(_g + vob1, _l + 8192); } while (0)
; #define LDA(dst, b, h) _Pragma("unroll") for (int m = 0; m < 4; ++m) _Pragma("unroll") for (int k = 0; k < 2; ++k) dst[m][k] = *(const LAS bf16x8*)(la + ((b) * 2 + (h)) * 16384 + m * 2048 + k * 1024)
; #define LDB(dst, b, h) _Pragma("unroll") for (int n = 0; n < 2; ++n) _Pragma("unroll") for (int k = 0; k < 2; ++k) dst[n][k] = *(const LAS bf16x8*)(lb + ((b) * 2 + (h)) * 16384 + n * 2048 + k * 1024)
; #define MMA(ai, bj, Af, Bf) do { __builtin_amdgcn_s_setprio(1); \
;     _Pragma("unroll") for (int m = 0; m < 4; ++m) _Pragma("unroll") for (int n = 0; n < 2; ++n) _Pragma("unroll") for (int k = 0; k < 2; ++k) \
;         acc[ai][bj][m][n] = __builtin_amdgcn_mfma_f32_16x16x32_bf16(Bf[n][k], Af[m][k], acc[ai][bj][m][n], 0, 0, 0); \
;     __builtin_amdgcn_s_setprio(0); } while (0)
; template <int BMODE, class Epi, class TileFn>
; DEV void gemm_loop(LAS unsigned char* lds, const bf16_t* __restrict__ A, int lda, const bf16_t* __restrict__ B, int ldb, int K, const Epi& epi, int t0, int tstep, int tend, const TileFn& tf) {
;     ...
;             LDB(B0, 1, 0); LDB(B1, 1, 1); SCHED; LDA(At, 1, 0); STG_A(0, 1, a2);
;             WAIT_V(8); WAIT_L(0); BAR; MMA(0, 0, At, B0); MMA(0, 1, At, B1); BAR; SCHED;
;             LDA(At, 1, 1); STG_B(1, 0, b3); STG_B(1, 1, b3); STG_A(1, 0, a3);
;             WAIT_V(8); WAIT_L(0); BAR; MMA(1, 0, At, B0); MMA(1, 1, At, B1); BAR; SCHED;
;         }
;         if (wr == 0) BAR;
	s_waitcnt lgkmcnt(0)
	v_mfma_f32_16x16x32_bf16 v[124:127], v[162:165], v[212:215], v[124:127]
	v_mfma_f32_16x16x32_bf16 v[120:123], v[170:173], v[212:215], v[120:123]
	v_mfma_f32_16x16x32_bf16 v[108:111], v[162:165], v[220:223], v[108:111]
	v_mfma_f32_16x16x32_bf16 v[104:107], v[170:173], v[220:223], v[104:107]
	v_mfma_f32_16x16x32_bf16 v[92:95], v[162:165], v[228:231], v[92:95]
	v_mfma_f32_16x16x32_bf16 v[88:91], v[170:173], v[228:231], v[88:91]
	v_mfma_f32_16x16x32_bf16 v[76:79], v[162:165], v[236:239], v[76:79]
	v_mfma_f32_16x16x32_bf16 v[72:75], v[170:173], v[236:239], v[72:75]
	v_mfma_f32_16x16x32_bf16 v[124:127], v[166:169], v[216:219], v[124:127]
	v_mfma_f32_16x16x32_bf16 v[120:123], v[174:177], v[216:219], v[120:123]
	v_mfma_f32_16x16x32_bf16 v[108:111], v[166:169], v[224:227], v[108:111]
	v_mfma_f32_16x16x32_bf16 v[104:107], v[174:177], v[224:227], v[104:107]
	v_mfma_f32_16x16x32_bf16 v[92:95], v[166:169], v[232:235], v[92:95]
	v_mfma_f32_16x16x32_bf16 v[88:91], v[174:177], v[232:235], v[88:91]
	v_mfma_f32_16x16x32_bf16 v[76:79], v[166:169], v[240:243], v[76:79]
	v_mfma_f32_16x16x32_bf16 v[72:75], v[174:177], v[240:243], v[72:75]
	v_mfma_f32_16x16x32_bf16 v[116:119], v[178:181], v[212:215], v[116:119]
	v_mfma_f32_16x16x32_bf16 v[112:115], v[196:199], v[212:215], v[112:115]
	v_mfma_f32_16x16x32_bf16 v[100:103], v[178:181], v[220:223], v[100:103]
	v_mfma_f32_16x16x32_bf16 v[96:99], v[196:199], v[220:223], v[96:99]
	v_mfma_f32_16x16x32_bf16 v[84:87], v[178:181], v[228:231], v[84:87]
	v_mfma_f32_16x16x32_bf16 v[80:83], v[196:199], v[228:231], v[80:83]
	v_mfma_f32_16x16x32_bf16 v[68:71], v[178:181], v[236:239], v[68:71]
	v_mfma_f32_16x16x32_bf16 v[64:67], v[196:199], v[236:239], v[64:67]
	v_mfma_f32_16x16x32_bf16 v[116:119], v[182:185], v[216:219], v[116:119]
	v_mfma_f32_16x16x32_bf16 v[112:115], v[200:203], v[216:219], v[112:115]
	v_mfma_f32_16x16x32_bf16 v[100:103], v[182:185], v[224:227], v[100:103]
	v_mfma_f32_16x16x32_bf16 v[96:99], v[200:203], v[224:227], v[96:99]
	v_mfma_f32_16x16x32_bf16 v[84:87], v[182:185], v[232:235], v[84:87]
	v_mfma_f32_16x16x32_bf16 v[80:83], v[200:203], v[232:235], v[80:83]
	v_mfma_f32_16x16x32_bf16 v[68:71], v[182:185], v[240:243], v[68:71]
	v_mfma_f32_16x16x32_bf16 v[64:67], v[200:203], v[240:243], v[64:67]
	s_barrier
	v_readfirstlane_b32 s31, v153
	v_lshl_add_u64 v[186:187], v[186:187], 0, s[2:3]
	s_mov_b32 m0, s31
	v_readfirstlane_b32 s31, v154
	s_add_u32 s8, s8, 0x40080
	ds_read_b128 v[212:215], v161 offset:49152
	ds_read_b128 v[216:219], v161 offset:50176
	ds_read_b128 v[220:223], v161 offset:51200
	ds_read_b128 v[224:227], v161 offset:52224
	ds_read_b128 v[228:231], v161 offset:53248
	ds_read_b128 v[232:235], v161 offset:54272
	ds_read_b128 v[236:239], v161 offset:55296
	ds_read_b128 v[240:243], v161 offset:56320
	global_load_lds_dwordx4 v[186:187], off
	v_lshl_add_u64 v[186:187], v[204:205], 0, s[2:3]
	s_mov_b32 m0, s31
	s_addc_u32 s9, s9, 0
	v_readfirstlane_b32 s31, v157
	global_load_lds_dwordx4 v[186:187], off
	v_lshl_add_u64 v[186:187], s[8:9], 0, v[130:131]
	s_mov_b32 m0, s31
	s_nop 0
	global_load_lds_dwordx4 v[186:187], off
	v_lshl_add_u64 v[186:187], s[8:9], 0, v[132:133]
	v_readfirstlane_b32 s8, v158
	s_mov_b32 m0, s8
	v_readfirstlane_b32 s8, v155
	global_load_lds_dwordx4 v[186:187], off
	v_lshl_add_u64 v[186:187], v[244:245], 0, s[2:3]
	s_mov_b32 m0, s8
	v_readfirstlane_b32 s8, v156
	global_load_lds_dwordx4 v[186:187], off
	v_lshl_add_u64 v[186:187], v[246:247], 0, s[2:3]
	s_mov_b32 m0, s8
	s_nop 0
	global_load_lds_dwordx4 v[186:187], off
	s_waitcnt vmcnt(8)
	s_waitcnt lgkmcnt(0)
	s_barrier
	s_waitcnt lgkmcnt(0)
	v_mfma_f32_16x16x32_bf16 v[60:63], v[162:165], v[212:215], v[60:63]
	v_mfma_f32_16x16x32_bf16 v[56:59], v[170:173], v[212:215], v[56:59]
	v_mfma_f32_16x16x32_bf16 v[44:47], v[162:165], v[220:223], v[44:47]
	v_mfma_f32_16x16x32_bf16 v[40:43], v[170:173], v[220:223], v[40:43]
	v_mfma_f32_16x16x32_bf16 v[28:31], v[162:165], v[228:231], v[28:31]
	v_mfma_f32_16x16x32_bf16 v[24:27], v[170:173], v[228:231], v[24:27]
	v_mfma_f32_16x16x32_bf16 v[12:15], v[162:165], v[236:239], v[12:15]
	v_mfma_f32_16x16x32_bf16 v[8:11], v[170:173], v[236:239], v[8:11]
	v_mfma_f32_16x16x32_bf16 v[60:63], v[166:169], v[216:219], v[60:63]
	v_mfma_f32_16x16x32_bf16 v[56:59], v[174:177], v[216:219], v[56:59]
	v_mfma_f32_16x16x32_bf16 v[44:47], v[166:169], v[224:227], v[44:47]
	v_mfma_f32_16x16x32_bf16 v[40:43], v[174:177], v[224:227], v[40:43]
	v_mfma_f32_16x16x32_bf16 v[28:31], v[166:169], v[232:235], v[28:31]
	v_mfma_f32_16x16x32_bf16 v[24:27], v[174:177], v[232:235], v[24:27]
	v_mfma_f32_16x16x32_bf16 v[12:15], v[166:169], v[240:243], v[12:15]
	v_mfma_f32_16x16x32_bf16 v[8:11], v[174:177], v[240:243], v[8:11]
	v_mfma_f32_16x16x32_bf16 v[52:55], v[178:181], v[212:215], v[52:55]
	v_mfma_f32_16x16x32_bf16 v[48:51], v[196:199], v[212:215], v[48:51]
	v_mfma_f32_16x16x32_bf16 v[36:39], v[178:181], v[220:223], v[36:39]
	v_mfma_f32_16x16x32_bf16 v[32:35], v[196:199], v[220:223], v[32:35]
	v_mfma_f32_16x16x32_bf16 v[20:23], v[178:181], v[228:231], v[20:23]
	v_mfma_f32_16x16x32_bf16 v[16:19], v[196:199], v[228:231], v[16:19]
	v_mfma_f32_16x16x32_bf16 v[4:7], v[178:181], v[236:239], v[4:7]
	v_mfma_f32_16x16x32_bf16 v[0:3], v[196:199], v[236:239], v[0:3]
	v_mfma_f32_16x16x32_bf16 v[52:55], v[182:185], v[216:219], v[52:55]
	v_mfma_f32_16x16x32_bf16 v[48:51], v[200:203], v[216:219], v[48:51]
	v_mfma_f32_16x16x32_bf16 v[36:39], v[182:185], v[224:227], v[36:39]
	v_mfma_f32_16x16x32_bf16 v[32:35], v[200:203], v[224:227], v[32:35]
	v_mfma_f32_16x16x32_bf16 v[20:23], v[182:185], v[232:235], v[20:23]
	v_mfma_f32_16x16x32_bf16 v[16:19], v[200:203], v[232:235], v[16:19]
	v_mfma_f32_16x16x32_bf16 v[4:7], v[182:185], v[240:243], v[4:7]
	v_mfma_f32_16x16x32_bf16 v[0:3], v[200:203], v[240:243], v[0:3]
	s_barrier
	s_add_i32 s92, s92, 2
	s_add_u32 s36, s36, 0x100
	s_addc_u32 s37, s37, 0
	s_cmp_gt_u32 s92, 13
	s_cbranch_scc0 .LBB0_441
	s_setprio 0
	s_and_saveexec_b64 s[8:9], s[42:43]
	s_cbranch_execz .LBB0_444
	s_barrier

; #define WAIT_V(n) asm volatile("s_waitcnt vmcnt(" #n ")" ::: "memory")
; #define WAIT_L(n) asm volatile("s_waitcnt lgkmcnt(" #n ")" ::: "memory")
; #define BAR __builtin_amdgcn_s_barrier()
; #define SCHED __builtin_amdgcn_sched_barrier(0)
; #define STG_A(b, h, ptr) do { const char* _g = (ptr) + (h) * ahalf; LAS unsigned char* _l = lw + ((b) * 2 + (h)) * 16384; GLDS(_g + voa0, _l); GLDS(_g + voa1, _l + 8192); } while (0)
; #define STG_B(b, h, ptr) do { const char* _g = (ptr) + (h) * bhalf; LAS unsigned char* _l = lw + 65536 + ((b) * 2 + (h)) * 16384; GLDS(_g + vob0, _l); GLDS(_g + vob1, _l + 8192); } while (0)
; #define LDA(dst, b, h) _Pragma("unroll") for (int m = 0; m < 4; ++m) _Pragma("unroll") for (int k = 0; k < 2; ++k) dst[m][k] = *(const LAS bf16x8*)(la + ((b) * 2 + (h)) * 16384 + m * 2048 + k * 1024)
;     DEV void prefetch(LAS unsigned char* lds, int brow, int par, int tid) const { if (tid < 256) GLDS(ss + (size_t)(brow + tid) * 4, lds + LDS_EX + par * 4096 + tid * 16); }
; template <int BMODE, class Epi, class TileFn>
; DEV void gemm_loop(LAS unsigned char* lds, const bf16_t* __restrict__ A, int lda, const bf16_t* __restrict__ B, int ldb, int K, const Epi& epi, int t0, int tstep, int tend, const TileFn& tf) {
;     ...
;     int par = 0;
;     for (int tt = t0;; tt += tstep, par ^= 1) {
;         const bool has_next = tt + tstep < tend;
;         epi.prefetch(lds, brow, par, tid);
;         int nrow = brow, ncol = bcol;
;         if (has_next) tf(tt + tstep, nrow, ncol);
;         const char* nA = (const char*)(A + (size_t)nrow * lda);
;         const char* nB = BMODE == 0 ? (const char*)(B + (size_t)ncol * ldb) : (const char*)(B + (size_t)ncol * 8);
;         for (int t = 0; t < nt; t += 2) {
;             const bool last = (t == nt - 2);
;             const char* a1 = cA + (size_t)(t + 1) * 128;
;             const char* a2 = last ? nA : cA + (size_t)(t + 2) * 128;
;             const char* b2 = last ? nB : cB + (size_t)(t + 2) * bks;
;             const char* a3 = a2 + 128; const char* b3 = b2 + bks;
;             LDB(B0, 0, 0); LDB(B1, 0, 1); SCHED; LDA(At, 0, 0); STG_A(1, 1, a1);
;             WAIT_V(8); WAIT_L(0); BAR; MMA(0, 0, At, B0); MMA(0, 1, At, B1); BAR; SCHED;
;             LDA(At, 0, 1); STG_B(0, 0, b2); STG_B(0, 1, b2); STG_A(0, 0, a2);
;             WAIT_V(8); WAIT_L(0); BAR; MMA(1, 0, At, B0); MMA(1, 1, At, B1); BAR; SCHED;
.LBB0_1238:
	s_ashr_i32 s49, s48, 31
	s_lshl_b64 s[54:55], s[48:49], 11
	s_add_u32 s28, s88, s54
	s_addc_u32 s29, s89, s55
	s_ashr_i32 s53, s52, 31
	s_lshl_b64 s[74:75], s[52:53], 11
	s_add_u32 s30, s38, s74
	s_addc_u32 s37, s39, s75
	s_add_u32 s49, s66, s8
	s_addc_u32 s50, s67, s9
	v_lshl_add_u64 v[120:121], v[200:201], 0, s[8:9]
	v_lshl_add_u64 v[122:123], v[202:203], 0, s[8:9]
	v_readlane_b32 s8, v254, 61
	s_add_u32 s53, s8, s0
	v_readlane_b32 s0, v254, 62
	s_addc_u32 s80, s0, s1
	s_mov_b32 s81, -2
	s_mov_b64 s[0:1], 0
	v_readfirstlane_b32 s100, v188
	s_nop 3
	s_cmp_lt_u32 s100, 0x100
	s_cbranch_scc1 .Lsp_1239
	s_setprio 1
.Lsp_1239:
	ds_read_b128 v[132:135], v225
	ds_read_b128 v[136:139], v225 offset:1024
	ds_read_b128 v[140:143], v225 offset:2048
	ds_read_b128 v[144:147], v225 offset:3072
	ds_read_b128 v[148:151], v225 offset:16384
	ds_read_b128 v[152:155], v225 offset:17408
	ds_read_b128 v[156:159], v225 offset:18432
	ds_read_b128 v[160:163], v225 offset:19456
	s_add_u32 s8, s49, s0
	s_addc_u32 s9, s50, s1
	s_add_u32 s8, s8, 0x18466100
	s_addc_u32 s9, s9, 0
	s_add_u32 s31, s53, s0
	s_addc_u32 s82, s80, s1
	s_cmpk_eq_i32 s0, 0x700
	s_cselect_b32 s77, s29, s9
	s_cselect_b32 s76, s28, s8
	s_cselect_b32 s9, s37, s82
	s_cselect_b32 s8, s30, s31
	v_add_u32_e32 v194, 0xc000, v211
	v_lshl_add_u64 v[204:205], v[120:121], 0, s[0:1]
	v_readfirstlane_b32 s31, v194
	v_add_u32_e32 v194, 0xe000, v211
	s_mov_b32 m0, s31
	v_readfirstlane_b32 s31, v194
	ds_read_b128 v[164:167], v226
	ds_read_b128 v[168:171], v226 offset:1024
	ds_read_b128 v[172:175], v226 offset:2048
	ds_read_b128 v[176:179], v226 offset:3072
	ds_read_b128 v[180:183], v226 offset:4096
	ds_read_b128 v[228:231], v226 offset:5120
	ds_read_b128 v[232:235], v226 offset:6144
	ds_read_b128 v[236:239], v226 offset:7168
	global_load_lds_dwordx4 v[204:205], off
	v_lshl_add_u64 v[204:205], v[122:123], 0, s[0:1]
	s_mov_b32 m0, s31
	s_nop 0
	global_load_lds_dwordx4 v[204:205], off
	s_waitcnt vmcnt(8)
	s_waitcnt lgkmcnt(0)
	s_barrier
	s_waitcnt lgkmcnt(0)
	v_mfma_f32_16x16x32_bf16 v[128:131], v[132:135], v[164:167], 0
	v_mfma_f32_16x16x32_bf16 v[124:127], v[140:143], v[164:167], 0
	v_mfma_f32_16x16x32_bf16 v[108:111], v[132:135], v[172:175], 0
	v_mfma_f32_16x16x32_bf16 v[104:107], v[140:143], v[172:175], 0
	v_mfma_f32_16x16x32_bf16 v[92:95], v[132:135], v[180:183], 0
	v_mfma_f32_16x16x32_bf16 v[88:91], v[140:143], v[180:183], 0
	v_mfma_f32_16x16x32_bf16 v[76:79], v[132:135], v[232:235], 0
	v_mfma_f32_16x16x32_bf16 v[72:75], v[140:143], v[232:235], 0
	v_mfma_f32_16x16x32_bf16 v[128:131], v[136:139], v[168:171], v[128:131]
	v_mfma_f32_16x16x32_bf16 v[124:127], v[144:147], v[168:171], v[124:127]
	v_mfma_f32_16x16x32_bf16 v[108:111], v[136:139], v[176:179], v[108:111]
	v_mfma_f32_16x16x32_bf16 v[104:107], v[144:147], v[176:179], v[104:107]
	v_mfma_f32_16x16x32_bf16 v[92:95], v[136:139], v[228:231], v[92:95]
	v_mfma_f32_16x16x32_bf16 v[88:91], v[144:147], v[228:231], v[88:91]
	v_mfma_f32_16x16x32_bf16 v[76:79], v[136:139], v[236:239], v[76:79]
	v_mfma_f32_16x16x32_bf16 v[72:75], v[144:147], v[236:239], v[72:75]
	v_mfma_f32_16x16x32_bf16 v[116:119], v[148:151], v[164:167], 0
	v_mfma_f32_16x16x32_bf16 v[112:115], v[156:159], v[164:167], 0
	v_mfma_f32_16x16x32_bf16 v[100:103], v[148:151], v[172:175], 0
	v_mfma_f32_16x16x32_bf16 v[96:99], v[156:159], v[172:175], 0
	v_mfma_f32_16x16x32_bf16 v[84:87], v[148:151], v[180:183], 0
	v_mfma_f32_16x16x32_bf16 v[80:83], v[156:159], v[180:183], 0
	v_mfma_f32_16x16x32_bf16 v[68:71], v[148:151], v[232:235], 0
	v_mfma_f32_16x16x32_bf16 v[64:67], v[156:159], v[232:235], 0
	v_mfma_f32_16x16x32_bf16 v[116:119], v[152:155], v[168:171], v[116:119]
	v_mfma_f32_16x16x32_bf16 v[112:115], v[160:163], v[168:171], v[112:115]
	v_mfma_f32_16x16x32_bf16 v[100:103], v[152:155], v[176:179], v[100:103]
	v_mfma_f32_16x16x32_bf16 v[96:99], v[160:163], v[176:179], v[96:99]
	v_mfma_f32_16x16x32_bf16 v[84:87], v[152:155], v[228:231], v[84:87]
	v_mfma_f32_16x16x32_bf16 v[80:83], v[160:163], v[228:231], v[80:83]
	v_mfma_f32_16x16x32_bf16 v[68:71], v[152:155], v[236:239], v[68:71]
	v_mfma_f32_16x16x32_bf16 v[64:67], v[160:163], v[236:239], v[64:67]
	s_barrier
	v_readfirstlane_b32 s31, v212
	v_lshl_add_u64 v[204:205], s[8:9], 0, v[196:197]
	s_mov_b32 m0, s31
	v_readfirstlane_b32 s31, v213
	s_add_u32 s82, s8, 0x40000
	ds_read_b128 v[164:167], v226 offset:16384
	ds_read_b128 v[168:171], v226 offset:17408
	ds_read_b128 v[172:175], v226 offset:18432
	ds_read_b128 v[176:179], v226 offset:19456
	ds_read_b128 v[180:183], v226 offset:20480
	ds_read_b128 v[228:231], v226 offset:21504
	ds_read_b128 v[232:235], v226 offset:22528
	ds_read_b128 v[236:239], v226 offset:23552
	global_load_lds_dwordx4 v[204:205], off
	v_lshl_add_u64 v[240:241], s[8:9], 0, v[198:199]
	s_mov_b32 m0, s31
	s_addc_u32 s83, s9, 0
	v_readfirstlane_b32 s31, v214
	global_load_lds_dwordx4 v[240:241], off
	v_lshl_add_u64 v[242:243], s[82:83], 0, v[196:197]
	s_mov_b32 m0, s31
	v_readfirstlane_b32 s31, v215
	global_load_lds_dwordx4 v[242:243], off
	v_lshl_add_u64 v[242:243], s[82:83], 0, v[198:199]
	s_mov_b32 m0, s31
	v_readfirstlane_b32 s31, v211
	global_load_lds_dwordx4 v[242:243], off
	v_lshl_add_u64 v[242:243], s[76:77], 0, v[184:185]
	s_mov_b32 m0, s31
	v_readfirstlane_b32 s31, v216
	global_load_lds_dwordx4 v[242:243], off
	v_lshl_add_u64 v[244:245], s[76:77], 0, v[186:187]
	s_mov_b32 m0, s31
	s_nop 0
	global_load_lds_dwordx4 v[244:245], off
	s_waitcnt vmcnt(8)
	s_waitcnt lgkmcnt(0)
	s_barrier
; #define WAIT_V(n) asm volatile("s_waitcnt vmcnt(" #n ")" ::: "memory")
; #define WAIT_L(n) asm volatile("s_waitcnt lgkmcnt(" #n ")" ::: "memory")
; #define BAR __builtin_amdgcn_s_barrier()
; #define SCHED __builtin_amdgcn_sched_barrier(0)
; #define STG_A(b, h, ptr) do { const char* _g = (ptr) + (h) * ahalf; LAS unsigned char* _l = lw + ((b) * 2 + (h)) * 16384; GLDS(_g + voa0, _l); GLDS(_g + voa1, _l + 8192); } while (0)
; #define STG_B(b, h, ptr) do { const char* _g = (ptr) + (h) * bhalf; LAS unsigned char* _l = lw + 65536 + ((b) * 2 + (h)) * 16384; GLDS(_g + vob0, _l); GLDS(_g + vob1, _l + 8192); } while (0)
; #define LDA(dst, b, h) _Pragma("unroll") for (int m = 0; m < 4; ++m) _Pragma("unroll") for (int k = 0; k < 2; ++k) dst[m][k] = *(const LAS bf16x8*)(la + ((b) * 2 + (h)) * 16384 + m * 2048 + k * 1024)
; #define LDB(dst, b, h) _Pragma("unroll") for (int n = 0; n < 2; ++n) _Pragma("unroll") for (int k = 0; k < 2; ++k) dst[n][k] = *(const LAS bf16x8*)(lb + ((b) * 2 + (h)) * 16384 + n * 2048 + k * 1024)
; #define MMA(ai, bj, Af, Bf) do { __builtin_amdgcn_s_setprio(1); \
;     _Pragma("unroll") for (int m = 0; m < 4; ++m) _Pragma("unroll") for (int n = 0; n < 2; ++n) _Pragma("unroll") for (int k = 0; k < 2; ++k) \
;         acc[ai][bj][m][n] = __builtin_amdgcn_mfma_f32_16x16x32_bf16(Bf[n][k], Af[m][k], acc[ai][bj][m][n], 0, 0, 0); \
;     __builtin_amdgcn_s_setprio(0); } while (0)
; template <int BMODE, class Epi, class TileFn>
; DEV void gemm_loop(LAS unsigned char* lds, const bf16_t* __restrict__ A, int lda, const bf16_t* __restrict__ B, int ldb, int K, const Epi& epi, int t0, int tstep, int tend, const TileFn& tf) {
;     ...
;             LDB(B0, 0, 0); LDB(B1, 0, 1); SCHED; LDA(At, 0, 0); STG_A(1, 1, a1);
;             WAIT_V(8); WAIT_L(0); BAR; MMA(0, 0, At, B0); MMA(0, 1, At, B1); BAR; SCHED;
;             LDA(At, 0, 1); STG_B(0, 0, b2); STG_B(0, 1, b2); STG_A(0, 0, a2);
;             WAIT_V(8); WAIT_L(0); BAR; MMA(1, 0, At, B0); MMA(1, 1, At, B1); BAR; SCHED;
	s_waitcnt lgkmcnt(0)
	v_mfma_f32_16x16x32_bf16 v[60:63], v[132:135], v[164:167], 0
	v_mfma_f32_16x16x32_bf16 v[56:59], v[140:143], v[164:167], 0
	v_mfma_f32_16x16x32_bf16 v[44:47], v[132:135], v[172:175], 0
	v_mfma_f32_16x16x32_bf16 v[40:43], v[140:143], v[172:175], 0
	v_mfma_f32_16x16x32_bf16 v[28:31], v[132:135], v[180:183], 0
	v_mfma_f32_16x16x32_bf16 v[24:27], v[140:143], v[180:183], 0
	v_mfma_f32_16x16x32_bf16 v[12:15], v[132:135], v[232:235], 0
	v_mfma_f32_16x16x32_bf16 v[8:11], v[140:143], v[232:235], 0
	v_mfma_f32_16x16x32_bf16 v[60:63], v[136:139], v[168:171], v[60:63]
	v_mfma_f32_16x16x32_bf16 v[56:59], v[144:147], v[168:171], v[56:59]
	v_mfma_f32_16x16x32_bf16 v[44:47], v[136:139], v[176:179], v[44:47]
	v_mfma_f32_16x16x32_bf16 v[40:43], v[144:147], v[176:179], v[40:43]
	v_mfma_f32_16x16x32_bf16 v[28:31], v[136:139], v[228:231], v[28:31]
	v_mfma_f32_16x16x32_bf16 v[24:27], v[144:147], v[228:231], v[24:27]
	v_mfma_f32_16x16x32_bf16 v[12:15], v[136:139], v[236:239], v[12:15]
	v_mfma_f32_16x16x32_bf16 v[8:11], v[144:147], v[236:239], v[8:11]
	v_mfma_f32_16x16x32_bf16 v[52:55], v[148:151], v[164:167], 0
	v_mfma_f32_16x16x32_bf16 v[48:51], v[156:159], v[164:167], 0
	v_mfma_f32_16x16x32_bf16 v[36:39], v[148:151], v[172:175], 0
	v_mfma_f32_16x16x32_bf16 v[32:35], v[156:159], v[172:175], 0
	v_mfma_f32_16x16x32_bf16 v[20:23], v[148:151], v[180:183], 0
	v_mfma_f32_16x16x32_bf16 v[16:19], v[156:159], v[180:183], 0
	v_mfma_f32_16x16x32_bf16 v[4:7], v[148:151], v[232:235], 0
	v_mfma_f32_16x16x32_bf16 v[0:3], v[156:159], v[232:235], 0
	v_mfma_f32_16x16x32_bf16 v[52:55], v[152:155], v[168:171], v[52:55]
	v_mfma_f32_16x16x32_bf16 v[48:51], v[160:163], v[168:171], v[48:51]
	v_mfma_f32_16x16x32_bf16 v[36:39], v[152:155], v[176:179], v[36:39]
	v_mfma_f32_16x16x32_bf16 v[32:35], v[160:163], v[176:179], v[32:35]
	v_mfma_f32_16x16x32_bf16 v[20:23], v[152:155], v[228:231], v[20:23]
	v_mfma_f32_16x16x32_bf16 v[16:19], v[160:163], v[228:231], v[16:19]
	v_mfma_f32_16x16x32_bf16 v[4:7], v[152:155], v[236:239], v[4:7]
	v_mfma_f32_16x16x32_bf16 v[0:3], v[160:163], v[236:239], v[0:3]
	s_barrier
	s_branch .Lkmid_1239
.LBB0_1239:
	ds_read_b128 v[132:135], v225
	ds_read_b128 v[136:139], v225 offset:1024
	ds_read_b128 v[140:143], v225 offset:2048
	ds_read_b128 v[144:147], v225 offset:3072
	ds_read_b128 v[148:151], v225 offset:16384
	ds_read_b128 v[152:155], v225 offset:17408
	ds_read_b128 v[156:159], v225 offset:18432
	ds_read_b128 v[160:163], v225 offset:19456
	s_add_u32 s8, s49, s0
	s_addc_u32 s9, s50, s1
	s_add_u32 s8, s8, 0x18466100
	s_addc_u32 s9, s9, 0
	s_add_u32 s31, s53, s0
	s_addc_u32 s82, s80, s1
	s_cmpk_eq_i32 s0, 0x700
	s_cselect_b32 s77, s29, s9
	s_cselect_b32 s76, s28, s8
	s_cselect_b32 s9, s37, s82
	s_cselect_b32 s8, s30, s31
	v_add_u32_e32 v194, 0xc000, v211
	v_lshl_add_u64 v[204:205], v[120:121], 0, s[0:1]
	v_readfirstlane_b32 s31, v194
	v_add_u32_e32 v194, 0xe000, v211
	s_mov_b32 m0, s31
	v_readfirstlane_b32 s31, v194
	ds_read_b128 v[164:167], v226
	ds_read_b128 v[168:171], v226 offset:1024
	ds_read_b128 v[172:175], v226 offset:2048
	ds_read_b128 v[176:179], v226 offset:3072
	ds_read_b128 v[180:183], v226 offset:4096
	ds_read_b128 v[228:231], v226 offset:5120
	ds_read_b128 v[232:235], v226 offset:6144
	ds_read_b128 v[236:239], v226 offset:7168
	global_load_lds_dwordx4 v[204:205], off
	v_lshl_add_u64 v[204:205], v[122:123], 0, s[0:1]
	s_mov_b32 m0, s31
	s_nop 0
	global_load_lds_dwordx4 v[204:205], off
	s_waitcnt vmcnt(8)
	s_waitcnt lgkmcnt(0)
	s_barrier
	s_waitcnt lgkmcnt(0)
	v_mfma_f32_16x16x32_bf16 v[128:131], v[132:135], v[164:167], v[128:131]
	v_mfma_f32_16x16x32_bf16 v[124:127], v[140:143], v[164:167], v[124:127]
	v_mfma_f32_16x16x32_bf16 v[108:111], v[132:135], v[172:175], v[108:111]
	v_mfma_f32_16x16x32_bf16 v[104:107], v[140:143], v[172:175], v[104:107]
	v_mfma_f32_16x16x32_bf16 v[92:95], v[132:135], v[180:183], v[92:95]
	v_mfma_f32_16x16x32_bf16 v[88:91], v[140:143], v[180:183], v[88:91]
	v_mfma_f32_16x16x32_bf16 v[76:79], v[132:135], v[232:235], v[76:79]
	v_mfma_f32_16x16x32_bf16 v[72:75], v[140:143], v[232:235], v[72:75]
	v_mfma_f32_16x16x32_bf16 v[128:131], v[136:139], v[168:171], v[128:131]
	v_mfma_f32_16x16x32_bf16 v[124:127], v[144:147], v[168:171], v[124:127]
	v_mfma_f32_16x16x32_bf16 v[108:111], v[136:139], v[176:179], v[108:111]
	v_mfma_f32_16x16x32_bf16 v[104:107], v[144:147], v[176:179], v[104:107]
	v_mfma_f32_16x16x32_bf16 v[92:95], v[136:139], v[228:231], v[92:95]
	v_mfma_f32_16x16x32_bf16 v[88:91], v[144:147], v[228:231], v[88:91]
	v_mfma_f32_16x16x32_bf16 v[76:79], v[136:139], v[236:239], v[76:79]
	v_mfma_f32_16x16x32_bf16 v[72:75], v[144:147], v[236:239], v[72:75]
	v_mfma_f32_16x16x32_bf16 v[116:119], v[148:151], v[164:167], v[116:119]
	v_mfma_f32_16x16x32_bf16 v[112:115], v[156:159], v[164:167], v[112:115]
	v_mfma_f32_16x16x32_bf16 v[100:103], v[148:151], v[172:175], v[100:103]
	v_mfma_f32_16x16x32_bf16 v[96:99], v[156:159], v[172:175], v[96:99]
	v_mfma_f32_16x16x32_bf16 v[84:87], v[148:151], v[180:183], v[84:87]
	v_mfma_f32_16x16x32_bf16 v[80:83], v[156:159], v[180:183], v[80:83]
	v_mfma_f32_16x16x32_bf16 v[68:71], v[148:151], v[232:235], v[68:71]
	v_mfma_f32_16x16x32_bf16 v[64:67], v[156:159], v[232:235], v[64:67]
	v_mfma_f32_16x16x32_bf16 v[116:119], v[152:155], v[168:171], v[116:119]
	v_mfma_f32_16x16x32_bf16 v[112:115], v[160:163], v[168:171], v[112:115]
	v_mfma_f32_16x16x32_bf16 v[100:103], v[152:155], v[176:179], v[100:103]
	v_mfma_f32_16x16x32_bf16 v[96:99], v[160:163], v[176:179], v[96:99]
	v_mfma_f32_16x16x32_bf16 v[84:87], v[152:155], v[228:231], v[84:87]
	v_mfma_f32_16x16x32_bf16 v[80:83], v[160:163], v[228:231], v[80:83]
	v_mfma_f32_16x16x32_bf16 v[68:71], v[152:155], v[236:239], v[68:71]
	v_mfma_f32_16x16x32_bf16 v[64:67], v[160:163], v[236:239], v[64:67]
	s_barrier
; #define WAIT_V(n) asm volatile("s_waitcnt vmcnt(" #n ")" ::: "memory")
; #define WAIT_L(n) asm volatile("s_waitcnt lgkmcnt(" #n ")" ::: "memory")
; #define BAR __builtin_amdgcn_s_barrier()
; #define SCHED __builtin_amdgcn_sched_barrier(0)
; #define STG_A(b, h, ptr) do { const char* _g = (ptr) + (h) * ahalf; LAS unsigned char* _l = lw + ((b) * 2 + (h)) * 16384; GLDS(_g + voa0, _l); GLDS(_g + voa1, _l + 8192); } while (0)
; #define STG_B(b, h, ptr) do { const char* _g = (ptr) + (h) * bhalf; LAS unsigned char* _l = lw + 65536 + ((b) * 2 + (h)) * 16384; GLDS(_g + vob0, _l); GLDS(_g + vob1, _l + 8192); } while (0)
; #define LDA(dst, b, h) _Pragma("unroll") for (int m = 0; m < 4; ++m) _Pragma("unroll") for (int k = 0; k < 2; ++k) dst[m][k] = *(const LAS bf16x8*)(la + ((b) * 2 + (h)) * 16384 + m * 2048 + k * 1024)
; #define LDB(dst, b, h) _Pragma("unroll") for (int n = 0; n < 2; ++n) _Pragma("unroll") for (int k = 0; k < 2; ++k) dst[n][k] = *(const LAS bf16x8*)(lb + ((b) * 2 + (h)) * 16384 + n * 2048 + k * 1024)
; #define MMA(ai, bj, Af, Bf) do { __builtin_amdgcn_s_setprio(1); \
;     _Pragma("unroll") for (int m = 0; m < 4; ++m) _Pragma("unroll") for (int n = 0; n < 2; ++n) _Pragma("unroll") for (int k = 0; k < 2; ++k) \
;         acc[ai][bj][m][n] = __builtin_amdgcn_mfma_f32_16x16x32_bf16(Bf[n][k], Af[m][k], acc[ai][bj][m][n], 0, 0, 0); \
;     __builtin_amdgcn_s_setprio(0); } while (0)
; template <int BMODE, class Epi, class TileFn>
; DEV void gemm_loop(LAS unsigned char* lds, const bf16_t* __restrict__ A, int lda, const bf16_t* __restrict__ B, int ldb, int K, const Epi& epi, int t0, int tstep, int tend, const TileFn& tf) {
;     ...
;             LDA(At, 0, 1); STG_B(0, 0, b2); STG_B(0, 1, b2); STG_A(0, 0, a2);
;             WAIT_V(8); WAIT_L(0); BAR; MMA(1, 0, At, B0); MMA(1, 1, At, B1); BAR; SCHED;
;             LDB(B0, 1, 0); LDB(B1, 1, 1); SCHED; LDA(At, 1, 0); STG_A(0, 1, a2);
;             WAIT_V(8); WAIT_L(0); BAR; MMA(0, 0, At, B0); MMA(0, 1, At, B1); BAR; SCHED;
	v_readfirstlane_b32 s31, v212
	v_lshl_add_u64 v[204:205], s[8:9], 0, v[196:197]
	s_mov_b32 m0, s31
	v_readfirstlane_b32 s31, v213
	s_add_u32 s82, s8, 0x40000
	ds_read_b128 v[164:167], v226 offset:16384
	ds_read_b128 v[168:171], v226 offset:17408
	ds_read_b128 v[172:175], v226 offset:18432
	ds_read_b128 v[176:179], v226 offset:19456
	ds_read_b128 v[180:183], v226 offset:20480
	ds_read_b128 v[228:231], v226 offset:21504
	ds_read_b128 v[232:235], v226 offset:22528
	ds_read_b128 v[236:239], v226 offset:23552
	global_load_lds_dwordx4 v[204:205], off
	v_lshl_add_u64 v[240:241], s[8:9], 0, v[198:199]
	s_mov_b32 m0, s31
	s_addc_u32 s83, s9, 0
	v_readfirstlane_b32 s31, v214
	global_load_lds_dwordx4 v[240:241], off
	v_lshl_add_u64 v[242:243], s[82:83], 0, v[196:197]
	s_mov_b32 m0, s31
	v_readfirstlane_b32 s31, v215
	global_load_lds_dwordx4 v[242:243], off
	v_lshl_add_u64 v[242:243], s[82:83], 0, v[198:199]
	s_mov_b32 m0, s31
	v_readfirstlane_b32 s31, v211
	global_load_lds_dwordx4 v[242:243], off
	v_lshl_add_u64 v[242:243], s[76:77], 0, v[184:185]
	s_mov_b32 m0, s31
	v_readfirstlane_b32 s31, v216
	global_load_lds_dwordx4 v[242:243], off
	v_lshl_add_u64 v[244:245], s[76:77], 0, v[186:187]
	s_mov_b32 m0, s31
	s_nop 0
	global_load_lds_dwordx4 v[244:245], off
	s_waitcnt vmcnt(8)
	s_waitcnt lgkmcnt(0)
	s_barrier
	s_waitcnt lgkmcnt(0)
	v_mfma_f32_16x16x32_bf16 v[60:63], v[132:135], v[164:167], v[60:63]
	v_mfma_f32_16x16x32_bf16 v[56:59], v[140:143], v[164:167], v[56:59]
	v_mfma_f32_16x16x32_bf16 v[44:47], v[132:135], v[172:175], v[44:47]
	v_mfma_f32_16x16x32_bf16 v[40:43], v[140:143], v[172:175], v[40:43]
	v_mfma_f32_16x16x32_bf16 v[28:31], v[132:135], v[180:183], v[28:31]
	v_mfma_f32_16x16x32_bf16 v[24:27], v[140:143], v[180:183], v[24:27]
	v_mfma_f32_16x16x32_bf16 v[12:15], v[132:135], v[232:235], v[12:15]
	v_mfma_f32_16x16x32_bf16 v[8:11], v[140:143], v[232:235], v[8:11]
	v_mfma_f32_16x16x32_bf16 v[60:63], v[136:139], v[168:171], v[60:63]
	v_mfma_f32_16x16x32_bf16 v[56:59], v[144:147], v[168:171], v[56:59]
	v_mfma_f32_16x16x32_bf16 v[44:47], v[136:139], v[176:179], v[44:47]
	v_mfma_f32_16x16x32_bf16 v[40:43], v[144:147], v[176:179], v[40:43]
	v_mfma_f32_16x16x32_bf16 v[28:31], v[136:139], v[228:231], v[28:31]
	v_mfma_f32_16x16x32_bf16 v[24:27], v[144:147], v[228:231], v[24:27]
	v_mfma_f32_16x16x32_bf16 v[12:15], v[136:139], v[236:239], v[12:15]
	v_mfma_f32_16x16x32_bf16 v[8:11], v[144:147], v[236:239], v[8:11]
	v_mfma_f32_16x16x32_bf16 v[52:55], v[148:151], v[164:167], v[52:55]
	v_mfma_f32_16x16x32_bf16 v[48:51], v[156:159], v[164:167], v[48:51]
	v_mfma_f32_16x16x32_bf16 v[36:39], v[148:151], v[172:175], v[36:39]
	v_mfma_f32_16x16x32_bf16 v[32:35], v[156:159], v[172:175], v[32:35]
	v_mfma_f32_16x16x32_bf16 v[20:23], v[148:151], v[180:183], v[20:23]
	v_mfma_f32_16x16x32_bf16 v[16:19], v[156:159], v[180:183], v[16:19]
	v_mfma_f32_16x16x32_bf16 v[4:7], v[148:151], v[232:235], v[4:7]
	v_mfma_f32_16x16x32_bf16 v[0:3], v[156:159], v[232:235], v[0:3]
	v_mfma_f32_16x16x32_bf16 v[52:55], v[152:155], v[168:171], v[52:55]
	v_mfma_f32_16x16x32_bf16 v[48:51], v[160:163], v[168:171], v[48:51]
	v_mfma_f32_16x16x32_bf16 v[36:39], v[152:155], v[176:179], v[36:39]
	v_mfma_f32_16x16x32_bf16 v[32:35], v[160:163], v[176:179], v[32:35]
	v_mfma_f32_16x16x32_bf16 v[20:23], v[152:155], v[228:231], v[20:23]
	v_mfma_f32_16x16x32_bf16 v[16:19], v[160:163], v[228:231], v[16:19]
	v_mfma_f32_16x16x32_bf16 v[4:7], v[152:155], v[236:239], v[4:7]
	v_mfma_f32_16x16x32_bf16 v[0:3], v[160:163], v[236:239], v[0:3]
	s_barrier
.Lkmid_1239:
	ds_read_b128 v[132:135], v225 offset:32768
	ds_read_b128 v[136:139], v225 offset:33792
	ds_read_b128 v[140:143], v225 offset:34816
	ds_read_b128 v[144:147], v225 offset:35840
	ds_read_b128 v[148:151], v225 offset:49152
	ds_read_b128 v[152:155], v225 offset:50176
	ds_read_b128 v[156:159], v225 offset:51200
	ds_read_b128 v[160:163], v225 offset:52224
	s_add_u32 s76, s76, 0x40000
	s_addc_u32 s77, s77, 0
	v_readfirstlane_b32 s31, v217
	v_lshl_add_u64 v[246:247], s[76:77], 0, v[184:185]
	s_mov_b32 m0, s31
	v_readfirstlane_b32 s31, v218
	ds_read_b128 v[164:167], v226 offset:32768
	ds_read_b128 v[168:171], v226 offset:33792
	ds_read_b128 v[172:175], v226 offset:34816
	ds_read_b128 v[176:179], v226 offset:35840
	ds_read_b128 v[180:183], v226 offset:36864
	ds_read_b128 v[228:231], v226 offset:37888
	ds_read_b128 v[232:235], v226 offset:38912
	ds_read_b128 v[236:239], v226 offset:39936
	global_load_lds_dwordx4 v[246:247], off
	v_lshl_add_u64 v[246:247], s[76:77], 0, v[186:187]
	s_mov_b32 m0, s31
	s_nop 0
	global_load_lds_dwordx4 v[246:247], off
	s_waitcnt vmcnt(8)
	s_waitcnt lgkmcnt(0)
	s_barrier
; #define WAIT_V(n) asm volatile("s_waitcnt vmcnt(" #n ")" ::: "memory")
; #define WAIT_L(n) asm volatile("s_waitcnt lgkmcnt(" #n ")" ::: "memory")
; #define BAR __builtin_amdgcn_s_barrier()
; #define SCHED __builtin_amdgcn_sched_barrier(0)
; #define STG_A(b, h, ptr) do { const char* _g = (ptr) + (h) * ahalf; LAS unsigned char* _l = lw + ((b) * 2 + (h)) * 16384; GLDS(_g + voa0, _l); GLDS(_g + voa1, _l + 8192); } while (0)
; #define STG_B(b, h, ptr) do { const char* _g = (ptr) + (h) * bhalf; LAS unsigned char* _l = lw + 65536 + ((b) * 2 + (h)) * 16384; GLDS(_g + vob0, _l); GLDS(_g + vob1, _l + 8192); } while (0)
; #define LDA(dst, b, h) _Pragma("unroll") for (int m = 0; m < 4; ++m) _Pragma("unroll") for (int k = 0; k < 2; ++k) dst[m][k] = *(const LAS bf16x8*)(la + ((b) * 2 + (h)) * 16384 + m * 2048 + k * 1024)
; #define LDB(dst, b, h) _Pragma("unroll") for (int n = 0; n < 2; ++n) _Pragma("unroll") for (int k = 0; k < 2; ++k) dst[n][k] = *(const LAS bf16x8*)(lb + ((b) * 2 + (h)) * 16384 + n * 2048 + k * 1024)
; #define MMA(ai, bj, Af, Bf) do { __builtin_amdgcn_s_setprio(1); \
;     _Pragma("unroll") for (int m = 0; m < 4; ++m) _Pragma("unroll") for (int n = 0; n < 2; ++n) _Pragma("unroll") for (int k = 0; k < 2; ++k) \
;         acc[ai][bj][m][n] = __builtin_amdgcn_mfma_f32_16x16x32_bf16(Bf[n][k], Af[m][k], acc[ai][bj][m][n], 0, 0, 0); \
;     __builtin_amdgcn_s_setprio(0); } while (0)
; template <int BMODE, class Epi, class TileFn>
; DEV void gemm_loop(LAS unsigned char* lds, const bf16_t* __restrict__ A, int lda, const bf16_t* __restrict__ B, int ldb, int K, const Epi& epi, int t0, int tstep, int tend, const TileFn& tf) {
;     ...
;             LDB(B0, 1, 0); LDB(B1, 1, 1); SCHED; LDA(At, 1, 0); STG_A(0, 1, a2);
;             WAIT_V(8); WAIT_L(0); BAR; MMA(0, 0, At, B0); MMA(0, 1, At, B1); BAR; SCHED;
;             LDA(At, 1, 1); STG_B(1, 0, b3); STG_B(1, 1, b3); STG_A(1, 0, a3);
;             WAIT_V(8); WAIT_L(0); BAR; MMA(1, 0, At, B0); MMA(1, 1, At, B1); BAR; SCHED;
;         }
;         if (wr == 0) BAR;
	s_waitcnt lgkmcnt(0)
	v_mfma_f32_16x16x32_bf16 v[128:131], v[132:135], v[164:167], v[128:131]
	v_mfma_f32_16x16x32_bf16 v[124:127], v[140:143], v[164:167], v[124:127]
	v_mfma_f32_16x16x32_bf16 v[108:111], v[132:135], v[172:175], v[108:111]
	v_mfma_f32_16x16x32_bf16 v[104:107], v[140:143], v[172:175], v[104:107]
	v_mfma_f32_16x16x32_bf16 v[92:95], v[132:135], v[180:183], v[92:95]
	v_mfma_f32_16x16x32_bf16 v[88:91], v[140:143], v[180:183], v[88:91]
	v_mfma_f32_16x16x32_bf16 v[76:79], v[132:135], v[232:235], v[76:79]
	v_mfma_f32_16x16x32_bf16 v[72:75], v[140:143], v[232:235], v[72:75]
	v_mfma_f32_16x16x32_bf16 v[128:131], v[136:139], v[168:171], v[128:131]
	v_mfma_f32_16x16x32_bf16 v[124:127], v[144:147], v[168:171], v[124:127]
	v_mfma_f32_16x16x32_bf16 v[108:111], v[136:139], v[176:179], v[108:111]
	v_mfma_f32_16x16x32_bf16 v[104:107], v[144:147], v[176:179], v[104:107]
	v_mfma_f32_16x16x32_bf16 v[92:95], v[136:139], v[228:231], v[92:95]
	v_mfma_f32_16x16x32_bf16 v[88:91], v[144:147], v[228:231], v[88:91]
	v_mfma_f32_16x16x32_bf16 v[76:79], v[136:139], v[236:239], v[76:79]
	v_mfma_f32_16x16x32_bf16 v[72:75], v[144:147], v[236:239], v[72:75]
	v_mfma_f32_16x16x32_bf16 v[116:119], v[148:151], v[164:167], v[116:119]
	v_mfma_f32_16x16x32_bf16 v[112:115], v[156:159], v[164:167], v[112:115]
	v_mfma_f32_16x16x32_bf16 v[100:103], v[148:151], v[172:175], v[100:103]
	v_mfma_f32_16x16x32_bf16 v[96:99], v[156:159], v[172:175], v[96:99]
	v_mfma_f32_16x16x32_bf16 v[84:87], v[148:151], v[180:183], v[84:87]
	v_mfma_f32_16x16x32_bf16 v[80:83], v[156:159], v[180:183], v[80:83]
	v_mfma_f32_16x16x32_bf16 v[68:71], v[148:151], v[232:235], v[68:71]
	v_mfma_f32_16x16x32_bf16 v[64:67], v[156:159], v[232:235], v[64:67]
	v_mfma_f32_16x16x32_bf16 v[116:119], v[152:155], v[168:171], v[116:119]
	v_mfma_f32_16x16x32_bf16 v[112:115], v[160:163], v[168:171], v[112:115]
	v_mfma_f32_16x16x32_bf16 v[100:103], v[152:155], v[176:179], v[100:103]
	v_mfma_f32_16x16x32_bf16 v[96:99], v[160:163], v[176:179], v[96:99]
	v_mfma_f32_16x16x32_bf16 v[84:87], v[152:155], v[228:231], v[84:87]
	v_mfma_f32_16x16x32_bf16 v[80:83], v[160:163], v[228:231], v[80:83]
	v_mfma_f32_16x16x32_bf16 v[68:71], v[152:155], v[236:239], v[68:71]
	v_mfma_f32_16x16x32_bf16 v[64:67], v[160:163], v[236:239], v[64:67]
	s_barrier
	v_readfirstlane_b32 s31, v219
	v_lshl_add_u64 v[204:205], v[204:205], 0, s[2:3]
	s_mov_b32 m0, s31
	v_readfirstlane_b32 s31, v220
	s_add_u32 s8, s8, 0x40080
	ds_read_b128 v[164:167], v226 offset:49152
	ds_read_b128 v[168:171], v226 offset:50176
	ds_read_b128 v[172:175], v226 offset:51200
	ds_read_b128 v[176:179], v226 offset:52224
	ds_read_b128 v[180:183], v226 offset:53248
	ds_read_b128 v[228:231], v226 offset:54272
	ds_read_b128 v[232:235], v226 offset:55296
	ds_read_b128 v[236:239], v226 offset:56320
	global_load_lds_dwordx4 v[204:205], off
	v_lshl_add_u64 v[204:205], v[240:241], 0, s[2:3]
	s_mov_b32 m0, s31
	s_addc_u32 s9, s9, 0
	v_readfirstlane_b32 s31, v223
	global_load_lds_dwordx4 v[204:205], off
	v_lshl_add_u64 v[204:205], s[8:9], 0, v[196:197]
	s_mov_b32 m0, s31
	s_nop 0
	global_load_lds_dwordx4 v[204:205], off
	v_lshl_add_u64 v[204:205], s[8:9], 0, v[198:199]
	v_readfirstlane_b32 s8, v224
	s_mov_b32 m0, s8
	v_readfirstlane_b32 s8, v221
	global_load_lds_dwordx4 v[204:205], off
	v_lshl_add_u64 v[204:205], v[242:243], 0, s[2:3]
	s_mov_b32 m0, s8
	v_readfirstlane_b32 s8, v222
	global_load_lds_dwordx4 v[204:205], off
	v_lshl_add_u64 v[204:205], v[244:245], 0, s[2:3]
	s_mov_b32 m0, s8
	s_nop 0
	global_load_lds_dwordx4 v[204:205], off
	s_waitcnt vmcnt(8)
	s_waitcnt lgkmcnt(0)
	s_barrier
	s_waitcnt lgkmcnt(0)
	v_mfma_f32_16x16x32_bf16 v[60:63], v[132:135], v[164:167], v[60:63]
	v_mfma_f32_16x16x32_bf16 v[56:59], v[140:143], v[164:167], v[56:59]
	v_mfma_f32_16x16x32_bf16 v[44:47], v[132:135], v[172:175], v[44:47]
	v_mfma_f32_16x16x32_bf16 v[40:43], v[140:143], v[172:175], v[40:43]
	v_mfma_f32_16x16x32_bf16 v[28:31], v[132:135], v[180:183], v[28:31]
	v_mfma_f32_16x16x32_bf16 v[24:27], v[140:143], v[180:183], v[24:27]
	v_mfma_f32_16x16x32_bf16 v[12:15], v[132:135], v[232:235], v[12:15]
	v_mfma_f32_16x16x32_bf16 v[8:11], v[140:143], v[232:235], v[8:11]
	v_mfma_f32_16x16x32_bf16 v[60:63], v[136:139], v[168:171], v[60:63]
	v_mfma_f32_16x16x32_bf16 v[56:59], v[144:147], v[168:171], v[56:59]
	v_mfma_f32_16x16x32_bf16 v[44:47], v[136:139], v[176:179], v[44:47]
	v_mfma_f32_16x16x32_bf16 v[40:43], v[144:147], v[176:179], v[40:43]
	v_mfma_f32_16x16x32_bf16 v[28:31], v[136:139], v[228:231], v[28:31]
	v_mfma_f32_16x16x32_bf16 v[24:27], v[144:147], v[228:231], v[24:27]
	v_mfma_f32_16x16x32_bf16 v[12:15], v[136:139], v[236:239], v[12:15]
	v_mfma_f32_16x16x32_bf16 v[8:11], v[144:147], v[236:239], v[8:11]
	v_mfma_f32_16x16x32_bf16 v[52:55], v[148:151], v[164:167], v[52:55]
	v_mfma_f32_16x16x32_bf16 v[48:51], v[156:159], v[164:167], v[48:51]
	v_mfma_f32_16x16x32_bf16 v[36:39], v[148:151], v[172:175], v[36:39]
	v_mfma_f32_16x16x32_bf16 v[32:35], v[156:159], v[172:175], v[32:35]
	v_mfma_f32_16x16x32_bf16 v[20:23], v[148:151], v[180:183], v[20:23]
	v_mfma_f32_16x16x32_bf16 v[16:19], v[156:159], v[180:183], v[16:19]
	v_mfma_f32_16x16x32_bf16 v[4:7], v[148:151], v[232:235], v[4:7]
	v_mfma_f32_16x16x32_bf16 v[0:3], v[156:159], v[232:235], v[0:3]
	v_mfma_f32_16x16x32_bf16 v[52:55], v[152:155], v[168:171], v[52:55]
	v_mfma_f32_16x16x32_bf16 v[48:51], v[160:163], v[168:171], v[48:51]
	v_mfma_f32_16x16x32_bf16 v[36:39], v[152:155], v[176:179], v[36:39]
	v_mfma_f32_16x16x32_bf16 v[32:35], v[160:163], v[176:179], v[32:35]
	v_mfma_f32_16x16x32_bf16 v[20:23], v[152:155], v[228:231], v[20:23]
	v_mfma_f32_16x16x32_bf16 v[16:19], v[160:163], v[228:231], v[16:19]
	v_mfma_f32_16x16x32_bf16 v[4:7], v[152:155], v[236:239], v[4:7]
	v_mfma_f32_16x16x32_bf16 v[0:3], v[160:163], v[236:239], v[0:3]
	s_barrier
	s_add_i32 s81, s81, 2
	s_add_u32 s0, s0, 0x100
	s_addc_u32 s1, s1, 0
	s_cmp_gt_u32 s81, 13
	s_cbranch_scc0 .LBB0_1239
	s_setprio 0
	s_and_saveexec_b64 s[0:1], s[44:45]
	s_cbranch_execz .LBB0_1242
	s_barrier

; #define WAIT_V(n) asm volatile("s_waitcnt vmcnt(" #n ")" ::: "memory")
; #define WAIT_L(n) asm volatile("s_waitcnt lgkmcnt(" #n ")" ::: "memory")
; #define BAR __builtin_amdgcn_s_barrier()
; #define SCHED __builtin_amdgcn_sched_barrier(0)
; #define STG_A(b, h, ptr) do { const char* _g = (ptr) + (h) * ahalf; LAS unsigned char* _l = lw + ((b) * 2 + (h)) * 16384; GLDS(_g + voa0, _l); GLDS(_g + voa1, _l + 8192); } while (0)
; #define STG_B(b, h, ptr) do { const char* _g = (ptr) + (h) * bhalf; LAS unsigned char* _l = lw + 65536 + ((b) * 2 + (h)) * 16384; GLDS(_g + vob0, _l); GLDS(_g + vob1, _l + 8192); } while (0)
; #define LDA(dst, b, h) _Pragma("unroll") for (int m = 0; m < 4; ++m) _Pragma("unroll") for (int k = 0; k < 2; ++k) dst[m][k] = *(const LAS bf16x8*)(la + ((b) * 2 + (h)) * 16384 + m * 2048 + k * 1024)
;     DEV void prefetch(LAS unsigned char* lds, int brow, int par, int tid) const { if (tid < 256) GLDS(ss + (size_t)(brow + tid) * 4, lds + LDS_EX + par * 4096 + tid * 16); }
; template <int BMODE, class Epi, class TileFn>
; DEV void gemm_loop(LAS unsigned char* lds, const bf16_t* __restrict__ A, int lda, const bf16_t* __restrict__ B, int ldb, int K, const Epi& epi, int t0, int tstep, int tend, const TileFn& tf) {
;     ...
;     int par = 0;
;     for (int tt = t0;; tt += tstep, par ^= 1) {
;         const bool has_next = tt + tstep < tend;
;         epi.prefetch(lds, brow, par, tid);
;         int nrow = brow, ncol = bcol;
;         if (has_next) tf(tt + tstep, nrow, ncol);
;         const char* nA = (const char*)(A + (size_t)nrow * lda);
;         const char* nB = BMODE == 0 ? (const char*)(B + (size_t)ncol * ldb) : (const char*)(B + (size_t)ncol * 8);
;         for (int t = 0; t < nt; t += 2) {
;             const bool last = (t == nt - 2);
;             const char* a1 = cA + (size_t)(t + 1) * 128;
;             const char* a2 = last ? nA : cA + (size_t)(t + 2) * 128;
;             const char* b2 = last ? nB : cB + (size_t)(t + 2) * bks;
;             const char* a3 = a2 + 128; const char* b3 = b2 + bks;
;             LDB(B0, 0, 0); LDB(B1, 0, 1); SCHED; LDA(At, 0, 0); STG_A(1, 1, a1);
;             WAIT_V(8); WAIT_L(0); BAR; MMA(0, 0, At, B0); MMA(0, 1, At, B1); BAR; SCHED;
;             LDA(At, 0, 1); STG_B(0, 0, b2); STG_B(0, 1, b2); STG_A(0, 0, a2);
;             WAIT_V(8); WAIT_L(0); BAR; MMA(1, 0, At, B0); MMA(1, 1, At, B1); BAR; SCHED;
.LBB0_1337:
	s_ashr_i32 s53, s52, 31
	s_lshl_b64 s[82:83], s[52:53], 11
	s_add_u32 s30, s72, s82
	s_addc_u32 s50, s73, s83
	s_ashr_i32 s81, s80, 31
	s_lshl_b64 s[40:41], s[80:81], 11
	s_add_u32 s53, s48, s40
	s_addc_u32 s74, s49, s41
	s_add_u32 s75, s66, s36
	s_addc_u32 s81, s67, s37
	v_readlane_b32 s31, v254, 63
	s_add_u32 s92, s31, s8
	v_readlane_b32 s8, v250, 0
	v_lshl_add_u64 v[136:137], v[132:133], 0, s[36:37]
	v_lshl_add_u64 v[138:139], v[134:135], 0, s[36:37]
	s_addc_u32 s93, s8, s9
	s_mov_b32 s94, -2
	s_mov_b64 s[36:37], 0
	v_readfirstlane_b32 s100, v188
	s_nop 3
	s_cmp_lt_u32 s100, 0x100
	s_cbranch_scc1 .Lsp_1338
	s_setprio 1
.Lsp_1338:
	ds_read_b128 v[158:161], v156
	ds_read_b128 v[162:165], v156 offset:1024
	ds_read_b128 v[166:169], v156 offset:2048
	ds_read_b128 v[170:173], v156 offset:3072
	ds_read_b128 v[174:177], v156 offset:16384
	ds_read_b128 v[178:181], v156 offset:17408
	ds_read_b128 v[182:185], v156 offset:18432
	ds_read_b128 v[196:199], v156 offset:19456
	s_add_u32 s8, s75, s36
	s_addc_u32 s9, s81, s37
	s_add_u32 s8, s8, 0x62e6100
	s_addc_u32 s9, s9, 0
	s_add_u32 s31, s92, s36
	s_addc_u32 s95, s93, s37
	s_cmpk_eq_i32 s36, 0x700
	s_cselect_b32 s55, s50, s9
	s_cselect_b32 s54, s30, s8
	s_cselect_b32 s9, s74, s95
	s_cselect_b32 s8, s53, s31
	v_add_u32_e32 v194, 0xc000, v141
	v_lshl_add_u64 v[186:187], v[136:137], 0, s[36:37]
	v_readfirstlane_b32 s31, v194
	v_add_u32_e32 v194, 0xe000, v141
	s_mov_b32 m0, s31
	v_readfirstlane_b32 s31, v194
	ds_read_b128 v[200:203], v157
	ds_read_b128 v[212:215], v157 offset:1024
	ds_read_b128 v[216:219], v157 offset:2048
	ds_read_b128 v[220:223], v157 offset:3072
	ds_read_b128 v[224:227], v157 offset:4096
	ds_read_b128 v[228:231], v157 offset:5120
	ds_read_b128 v[232:235], v157 offset:6144
	ds_read_b128 v[236:239], v157 offset:7168
	global_load_lds_dwordx4 v[186:187], off
	v_lshl_add_u64 v[186:187], v[138:139], 0, s[36:37]
	s_mov_b32 m0, s31
	s_nop 0
	global_load_lds_dwordx4 v[186:187], off
	s_waitcnt vmcnt(8)
	s_waitcnt lgkmcnt(0)
	s_barrier
	s_waitcnt lgkmcnt(0)
	v_mfma_f32_16x16x32_bf16 v[124:127], v[158:161], v[200:203], 0
	v_mfma_f32_16x16x32_bf16 v[120:123], v[166:169], v[200:203], 0
	v_mfma_f32_16x16x32_bf16 v[104:107], v[158:161], v[216:219], 0
	v_mfma_f32_16x16x32_bf16 v[108:111], v[166:169], v[216:219], 0
	v_mfma_f32_16x16x32_bf16 v[92:95], v[158:161], v[224:227], 0
	v_mfma_f32_16x16x32_bf16 v[88:91], v[166:169], v[224:227], 0
	v_mfma_f32_16x16x32_bf16 v[72:75], v[158:161], v[232:235], 0
	v_mfma_f32_16x16x32_bf16 v[76:79], v[166:169], v[232:235], 0
	v_mfma_f32_16x16x32_bf16 v[124:127], v[162:165], v[212:215], v[124:127]
	v_mfma_f32_16x16x32_bf16 v[120:123], v[170:173], v[212:215], v[120:123]
	v_mfma_f32_16x16x32_bf16 v[104:107], v[162:165], v[220:223], v[104:107]
	v_mfma_f32_16x16x32_bf16 v[108:111], v[170:173], v[220:223], v[108:111]
	v_mfma_f32_16x16x32_bf16 v[92:95], v[162:165], v[228:231], v[92:95]
	v_mfma_f32_16x16x32_bf16 v[88:91], v[170:173], v[228:231], v[88:91]
	v_mfma_f32_16x16x32_bf16 v[72:75], v[162:165], v[236:239], v[72:75]
	v_mfma_f32_16x16x32_bf16 v[76:79], v[170:173], v[236:239], v[76:79]
	v_mfma_f32_16x16x32_bf16 v[116:119], v[174:177], v[200:203], 0
	v_mfma_f32_16x16x32_bf16 v[112:115], v[182:185], v[200:203], 0
	v_mfma_f32_16x16x32_bf16 v[96:99], v[174:177], v[216:219], 0
	v_mfma_f32_16x16x32_bf16 v[100:103], v[182:185], v[216:219], 0
	v_mfma_f32_16x16x32_bf16 v[84:87], v[174:177], v[224:227], 0
	v_mfma_f32_16x16x32_bf16 v[80:83], v[182:185], v[224:227], 0
	v_mfma_f32_16x16x32_bf16 v[64:67], v[174:177], v[232:235], 0
	v_mfma_f32_16x16x32_bf16 v[68:71], v[182:185], v[232:235], 0
	v_mfma_f32_16x16x32_bf16 v[116:119], v[178:181], v[212:215], v[116:119]
	v_mfma_f32_16x16x32_bf16 v[112:115], v[196:199], v[212:215], v[112:115]
	v_mfma_f32_16x16x32_bf16 v[96:99], v[178:181], v[220:223], v[96:99]
	v_mfma_f32_16x16x32_bf16 v[100:103], v[196:199], v[220:223], v[100:103]
	v_mfma_f32_16x16x32_bf16 v[84:87], v[178:181], v[228:231], v[84:87]
	v_mfma_f32_16x16x32_bf16 v[80:83], v[196:199], v[228:231], v[80:83]
	v_mfma_f32_16x16x32_bf16 v[64:67], v[178:181], v[236:239], v[64:67]
	v_mfma_f32_16x16x32_bf16 v[68:71], v[196:199], v[236:239], v[68:71]
	s_barrier
	v_readfirstlane_b32 s31, v142
	v_lshl_add_u64 v[186:187], s[8:9], 0, v[128:129]
	s_mov_b32 m0, s31
	v_readfirstlane_b32 s31, v143
	s_add_u32 s96, s8, 0x40000
	ds_read_b128 v[200:203], v157 offset:16384
	ds_read_b128 v[212:215], v157 offset:17408
	ds_read_b128 v[216:219], v157 offset:18432
	ds_read_b128 v[220:223], v157 offset:19456
	ds_read_b128 v[224:227], v157 offset:20480
	ds_read_b128 v[228:231], v157 offset:21504
	ds_read_b128 v[232:235], v157 offset:22528
	ds_read_b128 v[236:239], v157 offset:23552
	global_load_lds_dwordx4 v[186:187], off
	v_lshl_add_u64 v[204:205], s[8:9], 0, v[130:131]
	s_mov_b32 m0, s31
	s_addc_u32 s97, s9, 0
	v_readfirstlane_b32 s31, v144
	global_load_lds_dwordx4 v[204:205], off
	v_lshl_add_u64 v[240:241], s[96:97], 0, v[128:129]
	s_mov_b32 m0, s31
	v_readfirstlane_b32 s31, v145
	global_load_lds_dwordx4 v[240:241], off
	v_lshl_add_u64 v[240:241], s[96:97], 0, v[130:131]
	s_mov_b32 m0, s31
	v_readfirstlane_b32 s31, v141
	global_load_lds_dwordx4 v[240:241], off
	v_lshl_add_u64 v[240:241], s[54:55], 0, v[128:129]
	s_mov_b32 m0, s31
	v_readfirstlane_b32 s31, v146
	global_load_lds_dwordx4 v[240:241], off
	v_lshl_add_u64 v[242:243], s[54:55], 0, v[130:131]
	s_mov_b32 m0, s31
	s_nop 0
	global_load_lds_dwordx4 v[242:243], off
	s_waitcnt vmcnt(8)
	s_waitcnt lgkmcnt(0)
	s_barrier
; #define WAIT_V(n) asm volatile("s_waitcnt vmcnt(" #n ")" ::: "memory")
; #define WAIT_L(n) asm volatile("s_waitcnt lgkmcnt(" #n ")" ::: "memory")
; #define BAR __builtin_amdgcn_s_barrier()
; #define SCHED __builtin_amdgcn_sched_barrier(0)
; #define STG_A(b, h, ptr) do { const char* _g = (ptr) + (h) * ahalf; LAS unsigned char* _l = lw + ((b) * 2 + (h)) * 16384; GLDS(_g + voa0, _l); GLDS(_g + voa1, _l + 8192); } while (0)
; #define STG_B(b, h, ptr) do { const char* _g = (ptr) + (h) * bhalf; LAS unsigned char* _l = lw + 65536 + ((b) * 2 + (h)) * 16384; GLDS(_g + vob0, _l); GLDS(_g + vob1, _l + 8192); } while (0)
; #define LDA(dst, b, h) _Pragma("unroll") for (int m = 0; m < 4; ++m) _Pragma("unroll") for (int k = 0; k < 2; ++k) dst[m][k] = *(const LAS bf16x8*)(la + ((b) * 2 + (h)) * 16384 + m * 2048 + k * 1024)
; #define LDB(dst, b, h) _Pragma("unroll") for (int n = 0; n < 2; ++n) _Pragma("unroll") for (int k = 0; k < 2; ++k) dst[n][k] = *(const LAS bf16x8*)(lb + ((b) * 2 + (h)) * 16384 + n * 2048 + k * 1024)
; #define MMA(ai, bj, Af, Bf) do { __builtin_amdgcn_s_setprio(1); \
;     _Pragma("unroll") for (int m = 0; m < 4; ++m) _Pragma("unroll") for (int n = 0; n < 2; ++n) _Pragma("unroll") for (int k = 0; k < 2; ++k) \
;         acc[ai][bj][m][n] = __builtin_amdgcn_mfma_f32_16x16x32_bf16(Bf[n][k], Af[m][k], acc[ai][bj][m][n], 0, 0, 0); \
;     __builtin_amdgcn_s_setprio(0); } while (0)
; template <int BMODE, class Epi, class TileFn>
; DEV void gemm_loop(LAS unsigned char* lds, const bf16_t* __restrict__ A, int lda, const bf16_t* __restrict__ B, int ldb, int K, const Epi& epi, int t0, int tstep, int tend, const TileFn& tf) {
;     ...
;             LDB(B0, 0, 0); LDB(B1, 0, 1); SCHED; LDA(At, 0, 0); STG_A(1, 1, a1);
;             WAIT_V(8); WAIT_L(0); BAR; MMA(0, 0, At, B0); MMA(0, 1, At, B1); BAR; SCHED;
;             LDA(At, 0, 1); STG_B(0, 0, b2); STG_B(0, 1, b2); STG_A(0, 0, a2);
;             WAIT_V(8); WAIT_L(0); BAR; MMA(1, 0, At, B0); MMA(1, 1, At, B1); BAR; SCHED;
	s_waitcnt lgkmcnt(0)
	v_mfma_f32_16x16x32_bf16 v[60:63], v[158:161], v[200:203], 0
	v_mfma_f32_16x16x32_bf16 v[56:59], v[166:169], v[200:203], 0
	v_mfma_f32_16x16x32_bf16 v[40:43], v[158:161], v[216:219], 0
	v_mfma_f32_16x16x32_bf16 v[44:47], v[166:169], v[216:219], 0
	v_mfma_f32_16x16x32_bf16 v[28:31], v[158:161], v[224:227], 0
	v_mfma_f32_16x16x32_bf16 v[24:27], v[166:169], v[224:227], 0
	v_mfma_f32_16x16x32_bf16 v[8:11], v[158:161], v[232:235], 0
	v_mfma_f32_16x16x32_bf16 v[12:15], v[166:169], v[232:235], 0
	v_mfma_f32_16x16x32_bf16 v[60:63], v[162:165], v[212:215], v[60:63]
	v_mfma_f32_16x16x32_bf16 v[56:59], v[170:173], v[212:215], v[56:59]
	v_mfma_f32_16x16x32_bf16 v[40:43], v[162:165], v[220:223], v[40:43]
	v_mfma_f32_16x16x32_bf16 v[44:47], v[170:173], v[220:223], v[44:47]
	v_mfma_f32_16x16x32_bf16 v[28:31], v[162:165], v[228:231], v[28:31]
	v_mfma_f32_16x16x32_bf16 v[24:27], v[170:173], v[228:231], v[24:27]
	v_mfma_f32_16x16x32_bf16 v[8:11], v[162:165], v[236:239], v[8:11]
	v_mfma_f32_16x16x32_bf16 v[12:15], v[170:173], v[236:239], v[12:15]
	v_mfma_f32_16x16x32_bf16 v[52:55], v[174:177], v[200:203], 0
	v_mfma_f32_16x16x32_bf16 v[48:51], v[182:185], v[200:203], 0
	v_mfma_f32_16x16x32_bf16 v[32:35], v[174:177], v[216:219], 0
	v_mfma_f32_16x16x32_bf16 v[36:39], v[182:185], v[216:219], 0
	v_mfma_f32_16x16x32_bf16 v[20:23], v[174:177], v[224:227], 0
	v_mfma_f32_16x16x32_bf16 v[16:19], v[182:185], v[224:227], 0
	v_mfma_f32_16x16x32_bf16 v[0:3], v[174:177], v[232:235], 0
	v_mfma_f32_16x16x32_bf16 v[4:7], v[182:185], v[232:235], 0
	v_mfma_f32_16x16x32_bf16 v[52:55], v[178:181], v[212:215], v[52:55]
	v_mfma_f32_16x16x32_bf16 v[48:51], v[196:199], v[212:215], v[48:51]
	v_mfma_f32_16x16x32_bf16 v[32:35], v[178:181], v[220:223], v[32:35]
	v_mfma_f32_16x16x32_bf16 v[36:39], v[196:199], v[220:223], v[36:39]
	v_mfma_f32_16x16x32_bf16 v[20:23], v[178:181], v[228:231], v[20:23]
	v_mfma_f32_16x16x32_bf16 v[16:19], v[196:199], v[228:231], v[16:19]
	v_mfma_f32_16x16x32_bf16 v[0:3], v[178:181], v[236:239], v[0:3]
	v_mfma_f32_16x16x32_bf16 v[4:7], v[196:199], v[236:239], v[4:7]
	s_barrier
	s_branch .Lkmid_1338
.LBB0_1338:
	ds_read_b128 v[158:161], v156
	ds_read_b128 v[162:165], v156 offset:1024
	ds_read_b128 v[166:169], v156 offset:2048
	ds_read_b128 v[170:173], v156 offset:3072
	ds_read_b128 v[174:177], v156 offset:16384
	ds_read_b128 v[178:181], v156 offset:17408
	ds_read_b128 v[182:185], v156 offset:18432
	ds_read_b128 v[196:199], v156 offset:19456
	s_add_u32 s8, s75, s36
	s_addc_u32 s9, s81, s37
	s_add_u32 s8, s8, 0x62e6100
	s_addc_u32 s9, s9, 0
	s_add_u32 s31, s92, s36
	s_addc_u32 s95, s93, s37
	s_cmpk_eq_i32 s36, 0x700
	s_cselect_b32 s55, s50, s9
	s_cselect_b32 s54, s30, s8
	s_cselect_b32 s9, s74, s95
	s_cselect_b32 s8, s53, s31
	v_add_u32_e32 v194, 0xc000, v141
	v_lshl_add_u64 v[186:187], v[136:137], 0, s[36:37]
	v_readfirstlane_b32 s31, v194
	v_add_u32_e32 v194, 0xe000, v141
	s_mov_b32 m0, s31
	v_readfirstlane_b32 s31, v194
	ds_read_b128 v[200:203], v157
	ds_read_b128 v[212:215], v157 offset:1024
	ds_read_b128 v[216:219], v157 offset:2048
	ds_read_b128 v[220:223], v157 offset:3072
	ds_read_b128 v[224:227], v157 offset:4096
	ds_read_b128 v[228:231], v157 offset:5120
	ds_read_b128 v[232:235], v157 offset:6144
	ds_read_b128 v[236:239], v157 offset:7168
	global_load_lds_dwordx4 v[186:187], off
	v_lshl_add_u64 v[186:187], v[138:139], 0, s[36:37]
	s_mov_b32 m0, s31
	s_nop 0
	global_load_lds_dwordx4 v[186:187], off
	s_waitcnt vmcnt(8)
	s_waitcnt lgkmcnt(0)
	s_barrier
	s_waitcnt lgkmcnt(0)
	v_mfma_f32_16x16x32_bf16 v[124:127], v[158:161], v[200:203], v[124:127]
	v_mfma_f32_16x16x32_bf16 v[120:123], v[166:169], v[200:203], v[120:123]
	v_mfma_f32_16x16x32_bf16 v[104:107], v[158:161], v[216:219], v[104:107]
	v_mfma_f32_16x16x32_bf16 v[108:111], v[166:169], v[216:219], v[108:111]
	v_mfma_f32_16x16x32_bf16 v[92:95], v[158:161], v[224:227], v[92:95]
	v_mfma_f32_16x16x32_bf16 v[88:91], v[166:169], v[224:227], v[88:91]
	v_mfma_f32_16x16x32_bf16 v[72:75], v[158:161], v[232:235], v[72:75]
	v_mfma_f32_16x16x32_bf16 v[76:79], v[166:169], v[232:235], v[76:79]
	v_mfma_f32_16x16x32_bf16 v[124:127], v[162:165], v[212:215], v[124:127]
	v_mfma_f32_16x16x32_bf16 v[120:123], v[170:173], v[212:215], v[120:123]
	v_mfma_f32_16x16x32_bf16 v[104:107], v[162:165], v[220:223], v[104:107]
	v_mfma_f32_16x16x32_bf16 v[108:111], v[170:173], v[220:223], v[108:111]
	v_mfma_f32_16x16x32_bf16 v[92:95], v[162:165], v[228:231], v[92:95]
	v_mfma_f32_16x16x32_bf16 v[88:91], v[170:173], v[228:231], v[88:91]
	v_mfma_f32_16x16x32_bf16 v[72:75], v[162:165], v[236:239], v[72:75]
	v_mfma_f32_16x16x32_bf16 v[76:79], v[170:173], v[236:239], v[76:79]
	v_mfma_f32_16x16x32_bf16 v[116:119], v[174:177], v[200:203], v[116:119]
	v_mfma_f32_16x16x32_bf16 v[112:115], v[182:185], v[200:203], v[112:115]
	v_mfma_f32_16x16x32_bf16 v[96:99], v[174:177], v[216:219], v[96:99]
	v_mfma_f32_16x16x32_bf16 v[100:103], v[182:185], v[216:219], v[100:103]
	v_mfma_f32_16x16x32_bf16 v[84:87], v[174:177], v[224:227], v[84:87]
	v_mfma_f32_16x16x32_bf16 v[80:83], v[182:185], v[224:227], v[80:83]
	v_mfma_f32_16x16x32_bf16 v[64:67], v[174:177], v[232:235], v[64:67]
	v_mfma_f32_16x16x32_bf16 v[68:71], v[182:185], v[232:235], v[68:71]
	v_mfma_f32_16x16x32_bf16 v[116:119], v[178:181], v[212:215], v[116:119]
	v_mfma_f32_16x16x32_bf16 v[112:115], v[196:199], v[212:215], v[112:115]
	v_mfma_f32_16x16x32_bf16 v[96:99], v[178:181], v[220:223], v[96:99]
	v_mfma_f32_16x16x32_bf16 v[100:103], v[196:199], v[220:223], v[100:103]
	v_mfma_f32_16x16x32_bf16 v[84:87], v[178:181], v[228:231], v[84:87]
	v_mfma_f32_16x16x32_bf16 v[80:83], v[196:199], v[228:231], v[80:83]
	v_mfma_f32_16x16x32_bf16 v[64:67], v[178:181], v[236:239], v[64:67]
	v_mfma_f32_16x16x32_bf16 v[68:71], v[196:199], v[236:239], v[68:71]
	s_barrier
; #define WAIT_V(n) asm volatile("s_waitcnt vmcnt(" #n ")" ::: "memory")
; #define WAIT_L(n) asm volatile("s_waitcnt lgkmcnt(" #n ")" ::: "memory")
; #define BAR __builtin_amdgcn_s_barrier()
; #define SCHED __builtin_amdgcn_sched_barrier(0)
; #define STG_A(b, h, ptr) do { const char* _g = (ptr) + (h) * ahalf; LAS unsigned char* _l = lw + ((b) * 2 + (h)) * 16384; GLDS(_g + voa0, _l); GLDS(_g + voa1, _l + 8192); } while (0)
; #define STG_B(b, h, ptr) do { const char* _g = (ptr) + (h) * bhalf; LAS unsigned char* _l = lw + 65536 + ((b) * 2 + (h)) * 16384; GLDS(_g + vob0, _l); GLDS(_g + vob1, _l + 8192); } while (0)
; #define LDA(dst, b, h) _Pragma("unroll") for (int m = 0; m < 4; ++m) _Pragma("unroll") for (int k = 0; k < 2; ++k) dst[m][k] = *(const LAS bf16x8*)(la + ((b) * 2 + (h)) * 16384 + m * 2048 + k * 1024)
; #define LDB(dst, b, h) _Pragma("unroll") for (int n = 0; n < 2; ++n) _Pragma("unroll") for (int k = 0; k < 2; ++k) dst[n][k] = *(const LAS bf16x8*)(lb + ((b) * 2 + (h)) * 16384 + n * 2048 + k * 1024)
; #define MMA(ai, bj, Af, Bf) do { __builtin_amdgcn_s_setprio(1); \
;     _Pragma("unroll") for (int m = 0; m < 4; ++m) _Pragma("unroll") for (int n = 0; n < 2; ++n) _Pragma("unroll") for (int k = 0; k < 2; ++k) \
;         acc[ai][bj][m][n] = __builtin_amdgcn_mfma_f32_16x16x32_bf16(Bf[n][k], Af[m][k], acc[ai][bj][m][n], 0, 0, 0); \
;     __builtin_amdgcn_s_setprio(0); } while (0)
; template <int BMODE, class Epi, class TileFn>
; DEV void gemm_loop(LAS unsigned char* lds, const bf16_t* __restrict__ A, int lda, const bf16_t* __restrict__ B, int ldb, int K, const Epi& epi, int t0, int tstep, int tend, const TileFn& tf) {
;     ...
;             LDA(At, 0, 1); STG_B(0, 0, b2); STG_B(0, 1, b2); STG_A(0, 0, a2);
;             WAIT_V(8); WAIT_L(0); BAR; MMA(1, 0, At, B0); MMA(1, 1, At, B1); BAR; SCHED;
;             LDB(B0, 1, 0); LDB(B1, 1, 1); SCHED; LDA(At, 1, 0); STG_A(0, 1, a2);
;             WAIT_V(8); WAIT_L(0); BAR; MMA(0, 0, At, B0); MMA(0, 1, At, B1); BAR; SCHED;
	v_readfirstlane_b32 s31, v142
	v_lshl_add_u64 v[186:187], s[8:9], 0, v[128:129]
	s_mov_b32 m0, s31
	v_readfirstlane_b32 s31, v143
	s_add_u32 s96, s8, 0x40000
	ds_read_b128 v[200:203], v157 offset:16384
	ds_read_b128 v[212:215], v157 offset:17408
	ds_read_b128 v[216:219], v157 offset:18432
	ds_read_b128 v[220:223], v157 offset:19456
	ds_read_b128 v[224:227], v157 offset:20480
	ds_read_b128 v[228:231], v157 offset:21504
	ds_read_b128 v[232:235], v157 offset:22528
	ds_read_b128 v[236:239], v157 offset:23552
	global_load_lds_dwordx4 v[186:187], off
	v_lshl_add_u64 v[204:205], s[8:9], 0, v[130:131]
	s_mov_b32 m0, s31
	s_addc_u32 s97, s9, 0
	v_readfirstlane_b32 s31, v144
	global_load_lds_dwordx4 v[204:205], off
	v_lshl_add_u64 v[240:241], s[96:97], 0, v[128:129]
	s_mov_b32 m0, s31
	v_readfirstlane_b32 s31, v145
	global_load_lds_dwordx4 v[240:241], off
	v_lshl_add_u64 v[240:241], s[96:97], 0, v[130:131]
	s_mov_b32 m0, s31
	v_readfirstlane_b32 s31, v141
	global_load_lds_dwordx4 v[240:241], off
	v_lshl_add_u64 v[240:241], s[54:55], 0, v[128:129]
	s_mov_b32 m0, s31
	v_readfirstlane_b32 s31, v146
	global_load_lds_dwordx4 v[240:241], off
	v_lshl_add_u64 v[242:243], s[54:55], 0, v[130:131]
	s_mov_b32 m0, s31
	s_nop 0
	global_load_lds_dwordx4 v[242:243], off
	s_waitcnt vmcnt(8)
	s_waitcnt lgkmcnt(0)
	s_barrier
	s_waitcnt lgkmcnt(0)
	v_mfma_f32_16x16x32_bf16 v[60:63], v[158:161], v[200:203], v[60:63]
	v_mfma_f32_16x16x32_bf16 v[56:59], v[166:169], v[200:203], v[56:59]
	v_mfma_f32_16x16x32_bf16 v[40:43], v[158:161], v[216:219], v[40:43]
	v_mfma_f32_16x16x32_bf16 v[44:47], v[166:169], v[216:219], v[44:47]
	v_mfma_f32_16x16x32_bf16 v[28:31], v[158:161], v[224:227], v[28:31]
	v_mfma_f32_16x16x32_bf16 v[24:27], v[166:169], v[224:227], v[24:27]
	v_mfma_f32_16x16x32_bf16 v[8:11], v[158:161], v[232:235], v[8:11]
	v_mfma_f32_16x16x32_bf16 v[12:15], v[166:169], v[232:235], v[12:15]
	v_mfma_f32_16x16x32_bf16 v[60:63], v[162:165], v[212:215], v[60:63]
	v_mfma_f32_16x16x32_bf16 v[56:59], v[170:173], v[212:215], v[56:59]
	v_mfma_f32_16x16x32_bf16 v[40:43], v[162:165], v[220:223], v[40:43]
	v_mfma_f32_16x16x32_bf16 v[44:47], v[170:173], v[220:223], v[44:47]
	v_mfma_f32_16x16x32_bf16 v[28:31], v[162:165], v[228:231], v[28:31]
	v_mfma_f32_16x16x32_bf16 v[24:27], v[170:173], v[228:231], v[24:27]
	v_mfma_f32_16x16x32_bf16 v[8:11], v[162:165], v[236:239], v[8:11]
	v_mfma_f32_16x16x32_bf16 v[12:15], v[170:173], v[236:239], v[12:15]
	v_mfma_f32_16x16x32_bf16 v[52:55], v[174:177], v[200:203], v[52:55]
	v_mfma_f32_16x16x32_bf16 v[48:51], v[182:185], v[200:203], v[48:51]
	v_mfma_f32_16x16x32_bf16 v[32:35], v[174:177], v[216:219], v[32:35]
	v_mfma_f32_16x16x32_bf16 v[36:39], v[182:185], v[216:219], v[36:39]
	v_mfma_f32_16x16x32_bf16 v[20:23], v[174:177], v[224:227], v[20:23]
	v_mfma_f32_16x16x32_bf16 v[16:19], v[182:185], v[224:227], v[16:19]
	v_mfma_f32_16x16x32_bf16 v[0:3], v[174:177], v[232:235], v[0:3]
	v_mfma_f32_16x16x32_bf16 v[4:7], v[182:185], v[232:235], v[4:7]
	v_mfma_f32_16x16x32_bf16 v[52:55], v[178:181], v[212:215], v[52:55]
	v_mfma_f32_16x16x32_bf16 v[48:51], v[196:199], v[212:215], v[48:51]
	v_mfma_f32_16x16x32_bf16 v[32:35], v[178:181], v[220:223], v[32:35]
	v_mfma_f32_16x16x32_bf16 v[36:39], v[196:199], v[220:223], v[36:39]
	v_mfma_f32_16x16x32_bf16 v[20:23], v[178:181], v[228:231], v[20:23]
	v_mfma_f32_16x16x32_bf16 v[16:19], v[196:199], v[228:231], v[16:19]
	v_mfma_f32_16x16x32_bf16 v[0:3], v[178:181], v[236:239], v[0:3]
	v_mfma_f32_16x16x32_bf16 v[4:7], v[196:199], v[236:239], v[4:7]
	s_barrier
.Lkmid_1338:
	ds_read_b128 v[158:161], v156 offset:32768
	ds_read_b128 v[162:165], v156 offset:33792
	ds_read_b128 v[166:169], v156 offset:34816
	ds_read_b128 v[170:173], v156 offset:35840
	ds_read_b128 v[174:177], v156 offset:49152
	ds_read_b128 v[178:181], v156 offset:50176
	ds_read_b128 v[182:185], v156 offset:51200
	ds_read_b128 v[196:199], v156 offset:52224
	s_add_u32 s54, s54, 0x40000
	s_addc_u32 s55, s55, 0
	v_readfirstlane_b32 s31, v147
	v_lshl_add_u64 v[244:245], s[54:55], 0, v[128:129]
	s_mov_b32 m0, s31
	v_readfirstlane_b32 s31, v148
	ds_read_b128 v[200:203], v157 offset:32768
	ds_read_b128 v[212:215], v157 offset:33792
	ds_read_b128 v[216:219], v157 offset:34816
	ds_read_b128 v[220:223], v157 offset:35840
	ds_read_b128 v[224:227], v157 offset:36864
	ds_read_b128 v[228:231], v157 offset:37888
	ds_read_b128 v[232:235], v157 offset:38912
	ds_read_b128 v[236:239], v157 offset:39936
	global_load_lds_dwordx4 v[244:245], off
	v_lshl_add_u64 v[244:245], s[54:55], 0, v[130:131]
	s_mov_b32 m0, s31
	s_nop 0
	global_load_lds_dwordx4 v[244:245], off
	s_waitcnt vmcnt(8)
	s_waitcnt lgkmcnt(0)
	s_barrier
; #define WAIT_V(n) asm volatile("s_waitcnt vmcnt(" #n ")" ::: "memory")
; #define WAIT_L(n) asm volatile("s_waitcnt lgkmcnt(" #n ")" ::: "memory")
; #define BAR __builtin_amdgcn_s_barrier()
; #define SCHED __builtin_amdgcn_sched_barrier(0)
; #define STG_A(b, h, ptr) do { const char* _g = (ptr) + (h) * ahalf; LAS unsigned char* _l = lw + ((b) * 2 + (h)) * 16384; GLDS(_g + voa0, _l); GLDS(_g + voa1, _l + 8192); } while (0)
; #define STG_B(b, h, ptr) do { const char* _g = (ptr) + (h) * bhalf; LAS unsigned char* _l = lw + 65536 + ((b) * 2 + (h)) * 16384; GLDS(_g + vob0, _l); GLDS(_g + vob1, _l + 8192); } while (0)
; #define LDA(dst, b, h) _Pragma("unroll") for (int m = 0; m < 4; ++m) _Pragma("unroll") for (int k = 0; k < 2; ++k) dst[m][k] = *(const LAS bf16x8*)(la + ((b) * 2 + (h)) * 16384 + m * 2048 + k * 1024)
; #define LDB(dst, b, h) _Pragma("unroll") for (int n = 0; n < 2; ++n) _Pragma("unroll") for (int k = 0; k < 2; ++k) dst[n][k] = *(const LAS bf16x8*)(lb + ((b) * 2 + (h)) * 16384 + n * 2048 + k * 1024)
; #define MMA(ai, bj, Af, Bf) do { __builtin_amdgcn_s_setprio(1); \
;     _Pragma("unroll") for (int m = 0; m < 4; ++m) _Pragma("unroll") for (int n = 0; n < 2; ++n) _Pragma("unroll") for (int k = 0; k < 2; ++k) \
;         acc[ai][bj][m][n] = __builtin_amdgcn_mfma_f32_16x16x32_bf16(Bf[n][k], Af[m][k], acc[ai][bj][m][n], 0, 0, 0); \
;     __builtin_amdgcn_s_setprio(0); } while (0)
; template <int BMODE, class Epi, class TileFn>
; DEV void gemm_loop(LAS unsigned char* lds, const bf16_t* __restrict__ A, int lda, const bf16_t* __restrict__ B, int ldb, int K, const Epi& epi, int t0, int tstep, int tend, const TileFn& tf) {
;     ...
;             LDB(B0, 1, 0); LDB(B1, 1, 1); SCHED; LDA(At, 1, 0); STG_A(0, 1, a2);
;             WAIT_V(8); WAIT_L(0); BAR; MMA(0, 0, At, B0); MMA(0, 1, At, B1); BAR; SCHED;
;             LDA(At, 1, 1); STG_B(1, 0, b3); STG_B(1, 1, b3); STG_A(1, 0, a3);
;             WAIT_V(8); WAIT_L(0); BAR; MMA(1, 0, At, B0); MMA(1, 1, At, B1); BAR; SCHED;
;         }
;         if (wr == 0) BAR;
	s_waitcnt lgkmcnt(0)
	v_mfma_f32_16x16x32_bf16 v[124:127], v[158:161], v[200:203], v[124:127]
	v_mfma_f32_16x16x32_bf16 v[120:123], v[166:169], v[200:203], v[120:123]
	v_mfma_f32_16x16x32_bf16 v[104:107], v[158:161], v[216:219], v[104:107]
	v_mfma_f32_16x16x32_bf16 v[108:111], v[166:169], v[216:219], v[108:111]
	v_mfma_f32_16x16x32_bf16 v[92:95], v[158:161], v[224:227], v[92:95]
	v_mfma_f32_16x16x32_bf16 v[88:91], v[166:169], v[224:227], v[88:91]
	v_mfma_f32_16x16x32_bf16 v[72:75], v[158:161], v[232:235], v[72:75]
	v_mfma_f32_16x16x32_bf16 v[76:79], v[166:169], v[232:235], v[76:79]
	v_mfma_f32_16x16x32_bf16 v[124:127], v[162:165], v[212:215], v[124:127]
	v_mfma_f32_16x16x32_bf16 v[120:123], v[170:173], v[212:215], v[120:123]
	v_mfma_f32_16x16x32_bf16 v[104:107], v[162:165], v[220:223], v[104:107]
	v_mfma_f32_16x16x32_bf16 v[108:111], v[170:173], v[220:223], v[108:111]
	v_mfma_f32_16x16x32_bf16 v[92:95], v[162:165], v[228:231], v[92:95]
	v_mfma_f32_16x16x32_bf16 v[88:91], v[170:173], v[228:231], v[88:91]
	v_mfma_f32_16x16x32_bf16 v[72:75], v[162:165], v[236:239], v[72:75]
	v_mfma_f32_16x16x32_bf16 v[76:79], v[170:173], v[236:239], v[76:79]
	v_mfma_f32_16x16x32_bf16 v[116:119], v[174:177], v[200:203], v[116:119]
	v_mfma_f32_16x16x32_bf16 v[112:115], v[182:185], v[200:203], v[112:115]
	v_mfma_f32_16x16x32_bf16 v[96:99], v[174:177], v[216:219], v[96:99]
	v_mfma_f32_16x16x32_bf16 v[100:103], v[182:185], v[216:219], v[100:103]
	v_mfma_f32_16x16x32_bf16 v[84:87], v[174:177], v[224:227], v[84:87]
	v_mfma_f32_16x16x32_bf16 v[80:83], v[182:185], v[224:227], v[80:83]
	v_mfma_f32_16x16x32_bf16 v[64:67], v[174:177], v[232:235], v[64:67]
	v_mfma_f32_16x16x32_bf16 v[68:71], v[182:185], v[232:235], v[68:71]
	v_mfma_f32_16x16x32_bf16 v[116:119], v[178:181], v[212:215], v[116:119]
	v_mfma_f32_16x16x32_bf16 v[112:115], v[196:199], v[212:215], v[112:115]
	v_mfma_f32_16x16x32_bf16 v[96:99], v[178:181], v[220:223], v[96:99]
	v_mfma_f32_16x16x32_bf16 v[100:103], v[196:199], v[220:223], v[100:103]
	v_mfma_f32_16x16x32_bf16 v[84:87], v[178:181], v[228:231], v[84:87]
	v_mfma_f32_16x16x32_bf16 v[80:83], v[196:199], v[228:231], v[80:83]
	v_mfma_f32_16x16x32_bf16 v[64:67], v[178:181], v[236:239], v[64:67]
	v_mfma_f32_16x16x32_bf16 v[68:71], v[196:199], v[236:239], v[68:71]
	s_barrier
	v_readfirstlane_b32 s31, v149
	v_lshl_add_u64 v[186:187], v[186:187], 0, s[2:3]
	s_mov_b32 m0, s31
	v_readfirstlane_b32 s31, v150
	s_add_u32 s8, s8, 0x40080
	ds_read_b128 v[200:203], v157 offset:49152
	ds_read_b128 v[212:215], v157 offset:50176
	ds_read_b128 v[216:219], v157 offset:51200
	ds_read_b128 v[220:223], v157 offset:52224
	ds_read_b128 v[224:227], v157 offset:53248
	ds_read_b128 v[228:231], v157 offset:54272
	ds_read_b128 v[232:235], v157 offset:55296
	ds_read_b128 v[236:239], v157 offset:56320
	global_load_lds_dwordx4 v[186:187], off
	v_lshl_add_u64 v[186:187], v[204:205], 0, s[2:3]
	s_mov_b32 m0, s31
	s_addc_u32 s9, s9, 0
	v_readfirstlane_b32 s31, v153
	global_load_lds_dwordx4 v[186:187], off
	v_lshl_add_u64 v[186:187], s[8:9], 0, v[128:129]
	s_mov_b32 m0, s31
	s_nop 0
	global_load_lds_dwordx4 v[186:187], off
	v_lshl_add_u64 v[186:187], s[8:9], 0, v[130:131]
	v_readfirstlane_b32 s8, v154
	s_mov_b32 m0, s8
	v_readfirstlane_b32 s8, v151
	global_load_lds_dwordx4 v[186:187], off
	v_lshl_add_u64 v[186:187], v[240:241], 0, s[2:3]
	s_mov_b32 m0, s8
	v_readfirstlane_b32 s8, v152
	global_load_lds_dwordx4 v[186:187], off
	v_lshl_add_u64 v[186:187], v[242:243], 0, s[2:3]
	s_mov_b32 m0, s8
	s_nop 0
	global_load_lds_dwordx4 v[186:187], off
	s_waitcnt vmcnt(8)
	s_waitcnt lgkmcnt(0)
	s_barrier
	s_waitcnt lgkmcnt(0)
	v_mfma_f32_16x16x32_bf16 v[60:63], v[158:161], v[200:203], v[60:63]
	v_mfma_f32_16x16x32_bf16 v[56:59], v[166:169], v[200:203], v[56:59]
	v_mfma_f32_16x16x32_bf16 v[40:43], v[158:161], v[216:219], v[40:43]
	v_mfma_f32_16x16x32_bf16 v[44:47], v[166:169], v[216:219], v[44:47]
	v_mfma_f32_16x16x32_bf16 v[28:31], v[158:161], v[224:227], v[28:31]
	v_mfma_f32_16x16x32_bf16 v[24:27], v[166:169], v[224:227], v[24:27]
	v_mfma_f32_16x16x32_bf16 v[8:11], v[158:161], v[232:235], v[8:11]
	v_mfma_f32_16x16x32_bf16 v[12:15], v[166:169], v[232:235], v[12:15]
	v_mfma_f32_16x16x32_bf16 v[60:63], v[162:165], v[212:215], v[60:63]
	v_mfma_f32_16x16x32_bf16 v[56:59], v[170:173], v[212:215], v[56:59]
	v_mfma_f32_16x16x32_bf16 v[40:43], v[162:165], v[220:223], v[40:43]
	v_mfma_f32_16x16x32_bf16 v[44:47], v[170:173], v[220:223], v[44:47]
	v_mfma_f32_16x16x32_bf16 v[28:31], v[162:165], v[228:231], v[28:31]
	v_mfma_f32_16x16x32_bf16 v[24:27], v[170:173], v[228:231], v[24:27]
	v_mfma_f32_16x16x32_bf16 v[8:11], v[162:165], v[236:239], v[8:11]
	v_mfma_f32_16x16x32_bf16 v[12:15], v[170:173], v[236:239], v[12:15]
	v_mfma_f32_16x16x32_bf16 v[52:55], v[174:177], v[200:203], v[52:55]
	v_mfma_f32_16x16x32_bf16 v[48:51], v[182:185], v[200:203], v[48:51]
	v_mfma_f32_16x16x32_bf16 v[32:35], v[174:177], v[216:219], v[32:35]
	v_mfma_f32_16x16x32_bf16 v[36:39], v[182:185], v[216:219], v[36:39]
	v_mfma_f32_16x16x32_bf16 v[20:23], v[174:177], v[224:227], v[20:23]
	v_mfma_f32_16x16x32_bf16 v[16:19], v[182:185], v[224:227], v[16:19]
	v_mfma_f32_16x16x32_bf16 v[0:3], v[174:177], v[232:235], v[0:3]
	v_mfma_f32_16x16x32_bf16 v[4:7], v[182:185], v[232:235], v[4:7]
	v_mfma_f32_16x16x32_bf16 v[52:55], v[178:181], v[212:215], v[52:55]
	v_mfma_f32_16x16x32_bf16 v[48:51], v[196:199], v[212:215], v[48:51]
	v_mfma_f32_16x16x32_bf16 v[32:35], v[178:181], v[220:223], v[32:35]
	v_mfma_f32_16x16x32_bf16 v[36:39], v[196:199], v[220:223], v[36:39]
	v_mfma_f32_16x16x32_bf16 v[20:23], v[178:181], v[228:231], v[20:23]
	v_mfma_f32_16x16x32_bf16 v[16:19], v[196:199], v[228:231], v[16:19]
	v_mfma_f32_16x16x32_bf16 v[0:3], v[178:181], v[236:239], v[0:3]
	v_mfma_f32_16x16x32_bf16 v[4:7], v[196:199], v[236:239], v[4:7]
	s_barrier
	s_add_i32 s94, s94, 2
	s_add_u32 s36, s36, 0x100
	s_addc_u32 s37, s37, 0
	s_cmp_gt_u32 s94, 13
	s_cbranch_scc0 .LBB0_1338
	s_setprio 0
	s_and_saveexec_b64 s[8:9], s[44:45]
	s_cbranch_execz .LBB0_1341
	s_barrier

; #define WAIT_V(n) asm volatile("s_waitcnt vmcnt(" #n ")" ::: "memory")
; #define WAIT_L(n) asm volatile("s_waitcnt lgkmcnt(" #n ")" ::: "memory")
; #define BAR __builtin_amdgcn_s_barrier()
; #define SCHED __builtin_amdgcn_sched_barrier(0)
; #define STG_A(b, h, ptr) do { const char* _g = (ptr) + (h) * ahalf; LAS unsigned char* _l = lw + ((b) * 2 + (h)) * 16384; GLDS(_g + voa0, _l); GLDS(_g + voa1, _l + 8192); } while (0)
; #define STG_B(b, h, ptr) do { const char* _g = (ptr) + (h) * bhalf; LAS unsigned char* _l = lw + 65536 + ((b) * 2 + (h)) * 16384; GLDS(_g + vob0, _l); GLDS(_g + vob1, _l + 8192); } while (0)
; #define LDA(dst, b, h) _Pragma("unroll") for (int m = 0; m < 4; ++m) _Pragma("unroll") for (int k = 0; k < 2; ++k) dst[m][k] = *(const LAS bf16x8*)(la + ((b) * 2 + (h)) * 16384 + m * 2048 + k * 1024)
;     DEV void prefetch(LAS unsigned char* lds, int brow, int par, int tid) const { if (tid < 256) GLDS(ss + (size_t)(brow + tid) * 4, lds + LDS_EX + par * 4096 + tid * 16); }
; template <int BMODE, class Epi, class TileFn>
; DEV void gemm_loop(LAS unsigned char* lds, const bf16_t* __restrict__ A, int lda, const bf16_t* __restrict__ B, int ldb, int K, const Epi& epi, int t0, int tstep, int tend, const TileFn& tf) {
;     ...
;     int par = 0;
;     for (int tt = t0;; tt += tstep, par ^= 1) {
;         const bool has_next = tt + tstep < tend;
;         epi.prefetch(lds, brow, par, tid);
;         int nrow = brow, ncol = bcol;
;         if (has_next) tf(tt + tstep, nrow, ncol);
;         const char* nA = (const char*)(A + (size_t)nrow * lda);
;         const char* nB = BMODE == 0 ? (const char*)(B + (size_t)ncol * ldb) : (const char*)(B + (size_t)ncol * 8);
;         for (int t = 0; t < nt; t += 2) {
;             const bool last = (t == nt - 2);
;             const char* a1 = cA + (size_t)(t + 1) * 128;
;             const char* a2 = last ? nA : cA + (size_t)(t + 2) * 128;
;             const char* b2 = last ? nB : cB + (size_t)(t + 2) * bks;
;             const char* a3 = a2 + 128; const char* b3 = b2 + bks;
;             LDB(B0, 0, 0); LDB(B1, 0, 1); SCHED; LDA(At, 0, 0); STG_A(1, 1, a1);
;             WAIT_V(8); WAIT_L(0); BAR; MMA(0, 0, At, B0); MMA(0, 1, At, B1); BAR; SCHED;
;             LDA(At, 0, 1); STG_B(0, 0, b2); STG_B(0, 1, b2); STG_A(0, 0, a2);
;             WAIT_V(8); WAIT_L(0); BAR; MMA(1, 0, At, B0); MMA(1, 1, At, B1); BAR; SCHED;
.LBB0_1440:
	s_mul_i32 s46, s7, 0x1600
	s_mul_hi_i32 s47, s7, 0x1600
	s_add_u32 s30, s70, s46
	s_addc_u32 s37, s71, s47
	s_mul_i32 s48, s28, 0x1600
	s_mul_hi_i32 s49, s28, 0x1600
	s_add_u32 s50, s42, s48
	s_addc_u32 s54, s43, s49
	s_add_u32 s55, s66, s8
	s_addc_u32 s74, s67, s9
	v_lshl_add_u64 v[120:121], v[200:201], 0, s[8:9]
	v_lshl_add_u64 v[122:123], v[202:203], 0, s[8:9]
	v_readlane_b32 s8, v250, 4
	s_add_u32 s75, s8, s0
	v_readlane_b32 s0, v250, 5
	s_addc_u32 s76, s0, s1
	s_mov_b32 s77, -2
	s_mov_b64 s[0:1], 0
	v_readfirstlane_b32 s100, v188
	s_nop 3
	s_cmp_lt_u32 s100, 0x100
	s_cbranch_scc1 .Lsp_1441
	s_setprio 1
.Lsp_1441:
	ds_read_b128 v[132:135], v225
	ds_read_b128 v[136:139], v225 offset:1024
	ds_read_b128 v[140:143], v225 offset:2048
	ds_read_b128 v[144:147], v225 offset:3072
	ds_read_b128 v[148:151], v225 offset:16384
	ds_read_b128 v[152:155], v225 offset:17408
	ds_read_b128 v[156:159], v225 offset:18432
	ds_read_b128 v[160:163], v225 offset:19456
	s_add_u32 s8, s55, s0
	s_addc_u32 s9, s74, s1
	s_add_u32 s8, s8, 0xc366100
	s_addc_u32 s9, s9, 0
	s_add_u32 s31, s75, s0
	s_addc_u32 s80, s76, s1
	s_cmpk_eq_i32 s0, 0x1500
	s_cselect_b32 s53, s37, s9
	s_cselect_b32 s52, s30, s8
	s_cselect_b32 s9, s54, s80
	s_cselect_b32 s8, s50, s31
	v_add_u32_e32 v194, 0xc000, v211
	v_lshl_add_u64 v[204:205], v[120:121], 0, s[0:1]
	v_readfirstlane_b32 s31, v194
	v_add_u32_e32 v194, 0xe000, v211
	s_mov_b32 m0, s31
	v_readfirstlane_b32 s31, v194
	ds_read_b128 v[164:167], v226
	ds_read_b128 v[168:171], v226 offset:1024
	ds_read_b128 v[172:175], v226 offset:2048
	ds_read_b128 v[176:179], v226 offset:3072
	ds_read_b128 v[180:183], v226 offset:4096
	ds_read_b128 v[228:231], v226 offset:5120
	ds_read_b128 v[232:235], v226 offset:6144
	ds_read_b128 v[236:239], v226 offset:7168
	global_load_lds_dwordx4 v[204:205], off
	v_lshl_add_u64 v[204:205], v[122:123], 0, s[0:1]
	s_mov_b32 m0, s31
	s_nop 0
	global_load_lds_dwordx4 v[204:205], off
	s_waitcnt vmcnt(8)
	s_waitcnt lgkmcnt(0)
	s_barrier
	s_waitcnt lgkmcnt(0)
	v_mfma_f32_16x16x32_bf16 v[128:131], v[132:135], v[164:167], 0
	v_mfma_f32_16x16x32_bf16 v[124:127], v[140:143], v[164:167], 0
	v_mfma_f32_16x16x32_bf16 v[108:111], v[132:135], v[172:175], 0
	v_mfma_f32_16x16x32_bf16 v[104:107], v[140:143], v[172:175], 0
	v_mfma_f32_16x16x32_bf16 v[92:95], v[132:135], v[180:183], 0
	v_mfma_f32_16x16x32_bf16 v[88:91], v[140:143], v[180:183], 0
	v_mfma_f32_16x16x32_bf16 v[76:79], v[132:135], v[232:235], 0
	v_mfma_f32_16x16x32_bf16 v[72:75], v[140:143], v[232:235], 0
	v_mfma_f32_16x16x32_bf16 v[128:131], v[136:139], v[168:171], v[128:131]
	v_mfma_f32_16x16x32_bf16 v[124:127], v[144:147], v[168:171], v[124:127]
	v_mfma_f32_16x16x32_bf16 v[108:111], v[136:139], v[176:179], v[108:111]
	v_mfma_f32_16x16x32_bf16 v[104:107], v[144:147], v[176:179], v[104:107]
	v_mfma_f32_16x16x32_bf16 v[92:95], v[136:139], v[228:231], v[92:95]
	v_mfma_f32_16x16x32_bf16 v[88:91], v[144:147], v[228:231], v[88:91]
	v_mfma_f32_16x16x32_bf16 v[76:79], v[136:139], v[236:239], v[76:79]
	v_mfma_f32_16x16x32_bf16 v[72:75], v[144:147], v[236:239], v[72:75]
	v_mfma_f32_16x16x32_bf16 v[116:119], v[148:151], v[164:167], 0
	v_mfma_f32_16x16x32_bf16 v[112:115], v[156:159], v[164:167], 0
	v_mfma_f32_16x16x32_bf16 v[100:103], v[148:151], v[172:175], 0
	v_mfma_f32_16x16x32_bf16 v[96:99], v[156:159], v[172:175], 0
	v_mfma_f32_16x16x32_bf16 v[84:87], v[148:151], v[180:183], 0
	v_mfma_f32_16x16x32_bf16 v[80:83], v[156:159], v[180:183], 0
	v_mfma_f32_16x16x32_bf16 v[68:71], v[148:151], v[232:235], 0
	v_mfma_f32_16x16x32_bf16 v[64:67], v[156:159], v[232:235], 0
	v_mfma_f32_16x16x32_bf16 v[116:119], v[152:155], v[168:171], v[116:119]
	v_mfma_f32_16x16x32_bf16 v[112:115], v[160:163], v[168:171], v[112:115]
	v_mfma_f32_16x16x32_bf16 v[100:103], v[152:155], v[176:179], v[100:103]
	v_mfma_f32_16x16x32_bf16 v[96:99], v[160:163], v[176:179], v[96:99]
	v_mfma_f32_16x16x32_bf16 v[84:87], v[152:155], v[228:231], v[84:87]
	v_mfma_f32_16x16x32_bf16 v[80:83], v[160:163], v[228:231], v[80:83]
	v_mfma_f32_16x16x32_bf16 v[68:71], v[152:155], v[236:239], v[68:71]
	v_mfma_f32_16x16x32_bf16 v[64:67], v[160:163], v[236:239], v[64:67]
	s_barrier
	v_readfirstlane_b32 s31, v212
	v_lshl_add_u64 v[204:205], s[8:9], 0, v[196:197]
	s_mov_b32 m0, s31
	v_readfirstlane_b32 s31, v213
	s_add_u32 s80, s8, 0xb0000
	ds_read_b128 v[164:167], v226 offset:16384
	ds_read_b128 v[168:171], v226 offset:17408
	ds_read_b128 v[172:175], v226 offset:18432
	ds_read_b128 v[176:179], v226 offset:19456
	ds_read_b128 v[180:183], v226 offset:20480
	ds_read_b128 v[228:231], v226 offset:21504
	ds_read_b128 v[232:235], v226 offset:22528
	ds_read_b128 v[236:239], v226 offset:23552
	global_load_lds_dwordx4 v[204:205], off
	v_lshl_add_u64 v[240:241], s[8:9], 0, v[198:199]
	s_mov_b32 m0, s31
	s_addc_u32 s81, s9, 0
	v_readfirstlane_b32 s31, v214
	global_load_lds_dwordx4 v[240:241], off
	v_lshl_add_u64 v[242:243], s[80:81], 0, v[196:197]
	s_mov_b32 m0, s31
	v_readfirstlane_b32 s31, v215
	global_load_lds_dwordx4 v[242:243], off
	v_lshl_add_u64 v[242:243], s[80:81], 0, v[198:199]
	s_mov_b32 m0, s31
	v_readfirstlane_b32 s31, v211
	global_load_lds_dwordx4 v[242:243], off
	v_lshl_add_u64 v[242:243], s[52:53], 0, v[184:185]
	s_mov_b32 m0, s31
	v_readfirstlane_b32 s31, v216
	global_load_lds_dwordx4 v[242:243], off
	v_lshl_add_u64 v[244:245], s[52:53], 0, v[186:187]
	s_mov_b32 m0, s31
	s_nop 0
	global_load_lds_dwordx4 v[244:245], off
	s_waitcnt vmcnt(8)
	s_waitcnt lgkmcnt(0)
	s_barrier
; #define WAIT_V(n) asm volatile("s_waitcnt vmcnt(" #n ")" ::: "memory")
; #define WAIT_L(n) asm volatile("s_waitcnt lgkmcnt(" #n ")" ::: "memory")
; #define BAR __builtin_amdgcn_s_barrier()
; #define SCHED __builtin_amdgcn_sched_barrier(0)
; #define STG_A(b, h, ptr) do { const char* _g = (ptr) + (h) * ahalf; LAS unsigned char* _l = lw + ((b) * 2 + (h)) * 16384; GLDS(_g + voa0, _l); GLDS(_g + voa1, _l + 8192); } while (0)
; #define STG_B(b, h, ptr) do { const char* _g = (ptr) + (h) * bhalf; LAS unsigned char* _l = lw + 65536 + ((b) * 2 + (h)) * 16384; GLDS(_g + vob0, _l); GLDS(_g + vob1, _l + 8192); } while (0)
; #define LDA(dst, b, h) _Pragma("unroll") for (int m = 0; m < 4; ++m) _Pragma("unroll") for (int k = 0; k < 2; ++k) dst[m][k] = *(const LAS bf16x8*)(la + ((b) * 2 + (h)) * 16384 + m * 2048 + k * 1024)
; #define LDB(dst, b, h) _Pragma("unroll") for (int n = 0; n < 2; ++n) _Pragma("unroll") for (int k = 0; k < 2; ++k) dst[n][k] = *(const LAS bf16x8*)(lb + ((b) * 2 + (h)) * 16384 + n * 2048 + k * 1024)
; #define MMA(ai, bj, Af, Bf) do { __builtin_amdgcn_s_setprio(1); \
;     _Pragma("unroll") for (int m = 0; m < 4; ++m) _Pragma("unroll") for (int n = 0; n < 2; ++n) _Pragma("unroll") for (int k = 0; k < 2; ++k) \
;         acc[ai][bj][m][n] = __builtin_amdgcn_mfma_f32_16x16x32_bf16(Bf[n][k], Af[m][k], acc[ai][bj][m][n], 0, 0, 0); \
;     __builtin_amdgcn_s_setprio(0); } while (0)
; template <int BMODE, class Epi, class TileFn>
; DEV void gemm_loop(LAS unsigned char* lds, const bf16_t* __restrict__ A, int lda, const bf16_t* __restrict__ B, int ldb, int K, const Epi& epi, int t0, int tstep, int tend, const TileFn& tf) {
;     ...
;             LDB(B0, 0, 0); LDB(B1, 0, 1); SCHED; LDA(At, 0, 0); STG_A(1, 1, a1);
;             WAIT_V(8); WAIT_L(0); BAR; MMA(0, 0, At, B0); MMA(0, 1, At, B1); BAR; SCHED;
;             LDA(At, 0, 1); STG_B(0, 0, b2); STG_B(0, 1, b2); STG_A(0, 0, a2);
;             WAIT_V(8); WAIT_L(0); BAR; MMA(1, 0, At, B0); MMA(1, 1, At, B1); BAR; SCHED;
	s_waitcnt lgkmcnt(0)
	v_mfma_f32_16x16x32_bf16 v[60:63], v[132:135], v[164:167], 0
	v_mfma_f32_16x16x32_bf16 v[56:59], v[140:143], v[164:167], 0
	v_mfma_f32_16x16x32_bf16 v[44:47], v[132:135], v[172:175], 0
	v_mfma_f32_16x16x32_bf16 v[40:43], v[140:143], v[172:175], 0
	v_mfma_f32_16x16x32_bf16 v[28:31], v[132:135], v[180:183], 0
	v_mfma_f32_16x16x32_bf16 v[24:27], v[140:143], v[180:183], 0
	v_mfma_f32_16x16x32_bf16 v[12:15], v[132:135], v[232:235], 0
	v_mfma_f32_16x16x32_bf16 v[8:11], v[140:143], v[232:235], 0
	v_mfma_f32_16x16x32_bf16 v[60:63], v[136:139], v[168:171], v[60:63]
	v_mfma_f32_16x16x32_bf16 v[56:59], v[144:147], v[168:171], v[56:59]
	v_mfma_f32_16x16x32_bf16 v[44:47], v[136:139], v[176:179], v[44:47]
	v_mfma_f32_16x16x32_bf16 v[40:43], v[144:147], v[176:179], v[40:43]
	v_mfma_f32_16x16x32_bf16 v[28:31], v[136:139], v[228:231], v[28:31]
	v_mfma_f32_16x16x32_bf16 v[24:27], v[144:147], v[228:231], v[24:27]
	v_mfma_f32_16x16x32_bf16 v[12:15], v[136:139], v[236:239], v[12:15]
	v_mfma_f32_16x16x32_bf16 v[8:11], v[144:147], v[236:239], v[8:11]
	v_mfma_f32_16x16x32_bf16 v[52:55], v[148:151], v[164:167], 0
	v_mfma_f32_16x16x32_bf16 v[48:51], v[156:159], v[164:167], 0
	v_mfma_f32_16x16x32_bf16 v[36:39], v[148:151], v[172:175], 0
	v_mfma_f32_16x16x32_bf16 v[32:35], v[156:159], v[172:175], 0
	v_mfma_f32_16x16x32_bf16 v[20:23], v[148:151], v[180:183], 0
	v_mfma_f32_16x16x32_bf16 v[16:19], v[156:159], v[180:183], 0
	v_mfma_f32_16x16x32_bf16 v[4:7], v[148:151], v[232:235], 0
	v_mfma_f32_16x16x32_bf16 v[0:3], v[156:159], v[232:235], 0
	v_mfma_f32_16x16x32_bf16 v[52:55], v[152:155], v[168:171], v[52:55]
	v_mfma_f32_16x16x32_bf16 v[48:51], v[160:163], v[168:171], v[48:51]
	v_mfma_f32_16x16x32_bf16 v[36:39], v[152:155], v[176:179], v[36:39]
	v_mfma_f32_16x16x32_bf16 v[32:35], v[160:163], v[176:179], v[32:35]
	v_mfma_f32_16x16x32_bf16 v[20:23], v[152:155], v[228:231], v[20:23]
	v_mfma_f32_16x16x32_bf16 v[16:19], v[160:163], v[228:231], v[16:19]
	v_mfma_f32_16x16x32_bf16 v[4:7], v[152:155], v[236:239], v[4:7]
	v_mfma_f32_16x16x32_bf16 v[0:3], v[160:163], v[236:239], v[0:3]
	s_barrier
	s_branch .Lkmid_1441
.LBB0_1441:
	ds_read_b128 v[132:135], v225
	ds_read_b128 v[136:139], v225 offset:1024
	ds_read_b128 v[140:143], v225 offset:2048
	ds_read_b128 v[144:147], v225 offset:3072
	ds_read_b128 v[148:151], v225 offset:16384
	ds_read_b128 v[152:155], v225 offset:17408
	ds_read_b128 v[156:159], v225 offset:18432
	ds_read_b128 v[160:163], v225 offset:19456
	s_add_u32 s8, s55, s0
	s_addc_u32 s9, s74, s1
	s_add_u32 s8, s8, 0xc366100
	s_addc_u32 s9, s9, 0
	s_add_u32 s31, s75, s0
	s_addc_u32 s80, s76, s1
	s_cmpk_eq_i32 s0, 0x1500
	s_cselect_b32 s53, s37, s9
	s_cselect_b32 s52, s30, s8
	s_cselect_b32 s9, s54, s80
	s_cselect_b32 s8, s50, s31
	v_add_u32_e32 v194, 0xc000, v211
	v_lshl_add_u64 v[204:205], v[120:121], 0, s[0:1]
	v_readfirstlane_b32 s31, v194
	v_add_u32_e32 v194, 0xe000, v211
	s_mov_b32 m0, s31
	v_readfirstlane_b32 s31, v194
	ds_read_b128 v[164:167], v226
	ds_read_b128 v[168:171], v226 offset:1024
	ds_read_b128 v[172:175], v226 offset:2048
	ds_read_b128 v[176:179], v226 offset:3072
	ds_read_b128 v[180:183], v226 offset:4096
	ds_read_b128 v[228:231], v226 offset:5120
	ds_read_b128 v[232:235], v226 offset:6144
	ds_read_b128 v[236:239], v226 offset:7168
	global_load_lds_dwordx4 v[204:205], off
	v_lshl_add_u64 v[204:205], v[122:123], 0, s[0:1]
	s_mov_b32 m0, s31
	s_nop 0
	global_load_lds_dwordx4 v[204:205], off
	s_waitcnt vmcnt(8)
	s_waitcnt lgkmcnt(0)
	s_barrier
	s_waitcnt lgkmcnt(0)
	v_mfma_f32_16x16x32_bf16 v[128:131], v[132:135], v[164:167], v[128:131]
	v_mfma_f32_16x16x32_bf16 v[124:127], v[140:143], v[164:167], v[124:127]
	v_mfma_f32_16x16x32_bf16 v[108:111], v[132:135], v[172:175], v[108:111]
	v_mfma_f32_16x16x32_bf16 v[104:107], v[140:143], v[172:175], v[104:107]
	v_mfma_f32_16x16x32_bf16 v[92:95], v[132:135], v[180:183], v[92:95]
	v_mfma_f32_16x16x32_bf16 v[88:91], v[140:143], v[180:183], v[88:91]
	v_mfma_f32_16x16x32_bf16 v[76:79], v[132:135], v[232:235], v[76:79]
	v_mfma_f32_16x16x32_bf16 v[72:75], v[140:143], v[232:235], v[72:75]
	v_mfma_f32_16x16x32_bf16 v[128:131], v[136:139], v[168:171], v[128:131]
	v_mfma_f32_16x16x32_bf16 v[124:127], v[144:147], v[168:171], v[124:127]
	v_mfma_f32_16x16x32_bf16 v[108:111], v[136:139], v[176:179], v[108:111]
	v_mfma_f32_16x16x32_bf16 v[104:107], v[144:147], v[176:179], v[104:107]
	v_mfma_f32_16x16x32_bf16 v[92:95], v[136:139], v[228:231], v[92:95]
	v_mfma_f32_16x16x32_bf16 v[88:91], v[144:147], v[228:231], v[88:91]
	v_mfma_f32_16x16x32_bf16 v[76:79], v[136:139], v[236:239], v[76:79]
	v_mfma_f32_16x16x32_bf16 v[72:75], v[144:147], v[236:239], v[72:75]
	v_mfma_f32_16x16x32_bf16 v[116:119], v[148:151], v[164:167], v[116:119]
	v_mfma_f32_16x16x32_bf16 v[112:115], v[156:159], v[164:167], v[112:115]
	v_mfma_f32_16x16x32_bf16 v[100:103], v[148:151], v[172:175], v[100:103]
	v_mfma_f32_16x16x32_bf16 v[96:99], v[156:159], v[172:175], v[96:99]
	v_mfma_f32_16x16x32_bf16 v[84:87], v[148:151], v[180:183], v[84:87]
	v_mfma_f32_16x16x32_bf16 v[80:83], v[156:159], v[180:183], v[80:83]
	v_mfma_f32_16x16x32_bf16 v[68:71], v[148:151], v[232:235], v[68:71]
	v_mfma_f32_16x16x32_bf16 v[64:67], v[156:159], v[232:235], v[64:67]
	v_mfma_f32_16x16x32_bf16 v[116:119], v[152:155], v[168:171], v[116:119]
	v_mfma_f32_16x16x32_bf16 v[112:115], v[160:163], v[168:171], v[112:115]
	v_mfma_f32_16x16x32_bf16 v[100:103], v[152:155], v[176:179], v[100:103]
	v_mfma_f32_16x16x32_bf16 v[96:99], v[160:163], v[176:179], v[96:99]
	v_mfma_f32_16x16x32_bf16 v[84:87], v[152:155], v[228:231], v[84:87]
	v_mfma_f32_16x16x32_bf16 v[80:83], v[160:163], v[228:231], v[80:83]
	v_mfma_f32_16x16x32_bf16 v[68:71], v[152:155], v[236:239], v[68:71]
	v_mfma_f32_16x16x32_bf16 v[64:67], v[160:163], v[236:239], v[64:67]
	s_barrier
; #define WAIT_V(n) asm volatile("s_waitcnt vmcnt(" #n ")" ::: "memory")
; #define WAIT_L(n) asm volatile("s_waitcnt lgkmcnt(" #n ")" ::: "memory")
; #define BAR __builtin_amdgcn_s_barrier()
; #define SCHED __builtin_amdgcn_sched_barrier(0)
; #define STG_A(b, h, ptr) do { const char* _g = (ptr) + (h) * ahalf; LAS unsigned char* _l = lw + ((b) * 2 + (h)) * 16384; GLDS(_g + voa0, _l); GLDS(_g + voa1, _l + 8192); } while (0)
; #define STG_B(b, h, ptr) do { const char* _g = (ptr) + (h) * bhalf; LAS unsigned char* _l = lw + 65536 + ((b) * 2 + (h)) * 16384; GLDS(_g + vob0, _l); GLDS(_g + vob1, _l + 8192); } while (0)
; #define LDA(dst, b, h) _Pragma("unroll") for (int m = 0; m < 4; ++m) _Pragma("unroll") for (int k = 0; k < 2; ++k) dst[m][k] = *(const LAS bf16x8*)(la + ((b) * 2 + (h)) * 16384 + m * 2048 + k * 1024)
; #define LDB(dst, b, h) _Pragma("unroll") for (int n = 0; n < 2; ++n) _Pragma("unroll") for (int k = 0; k < 2; ++k) dst[n][k] = *(const LAS bf16x8*)(lb + ((b) * 2 + (h)) * 16384 + n * 2048 + k * 1024)
; #define MMA(ai, bj, Af, Bf) do { __builtin_amdgcn_s_setprio(1); \
;     _Pragma("unroll") for (int m = 0; m < 4; ++m) _Pragma("unroll") for (int n = 0; n < 2; ++n) _Pragma("unroll") for (int k = 0; k < 2; ++k) \
;         acc[ai][bj][m][n] = __builtin_amdgcn_mfma_f32_16x16x32_bf16(Bf[n][k], Af[m][k], acc[ai][bj][m][n], 0, 0, 0); \
;     __builtin_amdgcn_s_setprio(0); } while (0)
; template <int BMODE, class Epi, class TileFn>
; DEV void gemm_loop(LAS unsigned char* lds, const bf16_t* __restrict__ A, int lda, const bf16_t* __restrict__ B, int ldb, int K, const Epi& epi, int t0, int tstep, int tend, const TileFn& tf) {
;     ...
;             LDA(At, 0, 1); STG_B(0, 0, b2); STG_B(0, 1, b2); STG_A(0, 0, a2);
;             WAIT_V(8); WAIT_L(0); BAR; MMA(1, 0, At, B0); MMA(1, 1, At, B1); BAR; SCHED;
;             LDB(B0, 1, 0); LDB(B1, 1, 1); SCHED; LDA(At, 1, 0); STG_A(0, 1, a2);
;             WAIT_V(8); WAIT_L(0); BAR; MMA(0, 0, At, B0); MMA(0, 1, At, B1); BAR; SCHED;
	v_readfirstlane_b32 s31, v212
	v_lshl_add_u64 v[204:205], s[8:9], 0, v[196:197]
	s_mov_b32 m0, s31
	v_readfirstlane_b32 s31, v213
	s_add_u32 s80, s8, 0xb0000
	ds_read_b128 v[164:167], v226 offset:16384
	ds_read_b128 v[168:171], v226 offset:17408
	ds_read_b128 v[172:175], v226 offset:18432
	ds_read_b128 v[176:179], v226 offset:19456
	ds_read_b128 v[180:183], v226 offset:20480
	ds_read_b128 v[228:231], v226 offset:21504
	ds_read_b128 v[232:235], v226 offset:22528
	ds_read_b128 v[236:239], v226 offset:23552
	global_load_lds_dwordx4 v[204:205], off
	v_lshl_add_u64 v[240:241], s[8:9], 0, v[198:199]
	s_mov_b32 m0, s31
	s_addc_u32 s81, s9, 0
	v_readfirstlane_b32 s31, v214
	global_load_lds_dwordx4 v[240:241], off
	v_lshl_add_u64 v[242:243], s[80:81], 0, v[196:197]
	s_mov_b32 m0, s31
	v_readfirstlane_b32 s31, v215
	global_load_lds_dwordx4 v[242:243], off
	v_lshl_add_u64 v[242:243], s[80:81], 0, v[198:199]
	s_mov_b32 m0, s31
	v_readfirstlane_b32 s31, v211
	global_load_lds_dwordx4 v[242:243], off
	v_lshl_add_u64 v[242:243], s[52:53], 0, v[184:185]
	s_mov_b32 m0, s31
	v_readfirstlane_b32 s31, v216
	global_load_lds_dwordx4 v[242:243], off
	v_lshl_add_u64 v[244:245], s[52:53], 0, v[186:187]
	s_mov_b32 m0, s31
	s_nop 0
	global_load_lds_dwordx4 v[244:245], off
	s_waitcnt vmcnt(8)
	s_waitcnt lgkmcnt(0)
	s_barrier
	s_waitcnt lgkmcnt(0)
	v_mfma_f32_16x16x32_bf16 v[60:63], v[132:135], v[164:167], v[60:63]
	v_mfma_f32_16x16x32_bf16 v[56:59], v[140:143], v[164:167], v[56:59]
	v_mfma_f32_16x16x32_bf16 v[44:47], v[132:135], v[172:175], v[44:47]
	v_mfma_f32_16x16x32_bf16 v[40:43], v[140:143], v[172:175], v[40:43]
	v_mfma_f32_16x16x32_bf16 v[28:31], v[132:135], v[180:183], v[28:31]
	v_mfma_f32_16x16x32_bf16 v[24:27], v[140:143], v[180:183], v[24:27]
	v_mfma_f32_16x16x32_bf16 v[12:15], v[132:135], v[232:235], v[12:15]
	v_mfma_f32_16x16x32_bf16 v[8:11], v[140:143], v[232:235], v[8:11]
	v_mfma_f32_16x16x32_bf16 v[60:63], v[136:139], v[168:171], v[60:63]
	v_mfma_f32_16x16x32_bf16 v[56:59], v[144:147], v[168:171], v[56:59]
	v_mfma_f32_16x16x32_bf16 v[44:47], v[136:139], v[176:179], v[44:47]
	v_mfma_f32_16x16x32_bf16 v[40:43], v[144:147], v[176:179], v[40:43]
	v_mfma_f32_16x16x32_bf16 v[28:31], v[136:139], v[228:231], v[28:31]
	v_mfma_f32_16x16x32_bf16 v[24:27], v[144:147], v[228:231], v[24:27]
	v_mfma_f32_16x16x32_bf16 v[12:15], v[136:139], v[236:239], v[12:15]
	v_mfma_f32_16x16x32_bf16 v[8:11], v[144:147], v[236:239], v[8:11]
	v_mfma_f32_16x16x32_bf16 v[52:55], v[148:151], v[164:167], v[52:55]
	v_mfma_f32_16x16x32_bf16 v[48:51], v[156:159], v[164:167], v[48:51]
	v_mfma_f32_16x16x32_bf16 v[36:39], v[148:151], v[172:175], v[36:39]
	v_mfma_f32_16x16x32_bf16 v[32:35], v[156:159], v[172:175], v[32:35]
	v_mfma_f32_16x16x32_bf16 v[20:23], v[148:151], v[180:183], v[20:23]
	v_mfma_f32_16x16x32_bf16 v[16:19], v[156:159], v[180:183], v[16:19]
	v_mfma_f32_16x16x32_bf16 v[4:7], v[148:151], v[232:235], v[4:7]
	v_mfma_f32_16x16x32_bf16 v[0:3], v[156:159], v[232:235], v[0:3]
	v_mfma_f32_16x16x32_bf16 v[52:55], v[152:155], v[168:171], v[52:55]
	v_mfma_f32_16x16x32_bf16 v[48:51], v[160:163], v[168:171], v[48:51]
	v_mfma_f32_16x16x32_bf16 v[36:39], v[152:155], v[176:179], v[36:39]
	v_mfma_f32_16x16x32_bf16 v[32:35], v[160:163], v[176:179], v[32:35]
	v_mfma_f32_16x16x32_bf16 v[20:23], v[152:155], v[228:231], v[20:23]
	v_mfma_f32_16x16x32_bf16 v[16:19], v[160:163], v[228:231], v[16:19]
	v_mfma_f32_16x16x32_bf16 v[4:7], v[152:155], v[236:239], v[4:7]
	v_mfma_f32_16x16x32_bf16 v[0:3], v[160:163], v[236:239], v[0:3]
	s_barrier
.Lkmid_1441:
	ds_read_b128 v[132:135], v225 offset:32768
	ds_read_b128 v[136:139], v225 offset:33792
	ds_read_b128 v[140:143], v225 offset:34816
	ds_read_b128 v[144:147], v225 offset:35840
	ds_read_b128 v[148:151], v225 offset:49152
	ds_read_b128 v[152:155], v225 offset:50176
	ds_read_b128 v[156:159], v225 offset:51200
	ds_read_b128 v[160:163], v225 offset:52224
	s_add_u32 s52, s52, 0xb0000
	s_addc_u32 s53, s53, 0
	v_readfirstlane_b32 s31, v217
	v_lshl_add_u64 v[246:247], s[52:53], 0, v[184:185]
	s_mov_b32 m0, s31
	v_readfirstlane_b32 s31, v218
	ds_read_b128 v[164:167], v226 offset:32768
	ds_read_b128 v[168:171], v226 offset:33792
	ds_read_b128 v[172:175], v226 offset:34816
	ds_read_b128 v[176:179], v226 offset:35840
	ds_read_b128 v[180:183], v226 offset:36864
	ds_read_b128 v[228:231], v226 offset:37888
	ds_read_b128 v[232:235], v226 offset:38912
	ds_read_b128 v[236:239], v226 offset:39936
	global_load_lds_dwordx4 v[246:247], off
	v_lshl_add_u64 v[246:247], s[52:53], 0, v[186:187]
	s_mov_b32 m0, s31
	s_nop 0
	global_load_lds_dwordx4 v[246:247], off
	s_waitcnt vmcnt(8)
	s_waitcnt lgkmcnt(0)
	s_barrier
; #define WAIT_V(n) asm volatile("s_waitcnt vmcnt(" #n ")" ::: "memory")
; #define WAIT_L(n) asm volatile("s_waitcnt lgkmcnt(" #n ")" ::: "memory")
; #define BAR __builtin_amdgcn_s_barrier()
; #define SCHED __builtin_amdgcn_sched_barrier(0)
; #define STG_A(b, h, ptr) do { const char* _g = (ptr) + (h) * ahalf; LAS unsigned char* _l = lw + ((b) * 2 + (h)) * 16384; GLDS(_g + voa0, _l); GLDS(_g + voa1, _l + 8192); } while (0)
; #define STG_B(b, h, ptr) do { const char* _g = (ptr) + (h) * bhalf; LAS unsigned char* _l = lw + 65536 + ((b) * 2 + (h)) * 16384; GLDS(_g + vob0, _l); GLDS(_g + vob1, _l + 8192); } while (0)
; #define LDA(dst, b, h) _Pragma("unroll") for (int m = 0; m < 4; ++m) _Pragma("unroll") for (int k = 0; k < 2; ++k) dst[m][k] = *(const LAS bf16x8*)(la + ((b) * 2 + (h)) * 16384 + m * 2048 + k * 1024)
; #define LDB(dst, b, h) _Pragma("unroll") for (int n = 0; n < 2; ++n) _Pragma("unroll") for (int k = 0; k < 2; ++k) dst[n][k] = *(const LAS bf16x8*)(lb + ((b) * 2 + (h)) * 16384 + n * 2048 + k * 1024)
; #define MMA(ai, bj, Af, Bf) do { __builtin_amdgcn_s_setprio(1); \
;     _Pragma("unroll") for (int m = 0; m < 4; ++m) _Pragma("unroll") for (int n = 0; n < 2; ++n) _Pragma("unroll") for (int k = 0; k < 2; ++k) \
;         acc[ai][bj][m][n] = __builtin_amdgcn_mfma_f32_16x16x32_bf16(Bf[n][k], Af[m][k], acc[ai][bj][m][n], 0, 0, 0); \
;     __builtin_amdgcn_s_setprio(0); } while (0)
; template <int BMODE, class Epi, class TileFn>
; DEV void gemm_loop(LAS unsigned char* lds, const bf16_t* __restrict__ A, int lda, const bf16_t* __restrict__ B, int ldb, int K, const Epi& epi, int t0, int tstep, int tend, const TileFn& tf) {
;     ...
;             LDB(B0, 1, 0); LDB(B1, 1, 1); SCHED; LDA(At, 1, 0); STG_A(0, 1, a2);
;             WAIT_V(8); WAIT_L(0); BAR; MMA(0, 0, At, B0); MMA(0, 1, At, B1); BAR; SCHED;
;             LDA(At, 1, 1); STG_B(1, 0, b3); STG_B(1, 1, b3); STG_A(1, 0, a3);
;             WAIT_V(8); WAIT_L(0); BAR; MMA(1, 0, At, B0); MMA(1, 1, At, B1); BAR; SCHED;
;         }
;         if (wr == 0) BAR;
	s_waitcnt lgkmcnt(0)
	v_mfma_f32_16x16x32_bf16 v[128:131], v[132:135], v[164:167], v[128:131]
	v_mfma_f32_16x16x32_bf16 v[124:127], v[140:143], v[164:167], v[124:127]
	v_mfma_f32_16x16x32_bf16 v[108:111], v[132:135], v[172:175], v[108:111]
	v_mfma_f32_16x16x32_bf16 v[104:107], v[140:143], v[172:175], v[104:107]
	v_mfma_f32_16x16x32_bf16 v[92:95], v[132:135], v[180:183], v[92:95]
	v_mfma_f32_16x16x32_bf16 v[88:91], v[140:143], v[180:183], v[88:91]
	v_mfma_f32_16x16x32_bf16 v[76:79], v[132:135], v[232:235], v[76:79]
	v_mfma_f32_16x16x32_bf16 v[72:75], v[140:143], v[232:235], v[72:75]
	v_mfma_f32_16x16x32_bf16 v[128:131], v[136:139], v[168:171], v[128:131]
	v_mfma_f32_16x16x32_bf16 v[124:127], v[144:147], v[168:171], v[124:127]
	v_mfma_f32_16x16x32_bf16 v[108:111], v[136:139], v[176:179], v[108:111]
	v_mfma_f32_16x16x32_bf16 v[104:107], v[144:147], v[176:179], v[104:107]
	v_mfma_f32_16x16x32_bf16 v[92:95], v[136:139], v[228:231], v[92:95]
	v_mfma_f32_16x16x32_bf16 v[88:91], v[144:147], v[228:231], v[88:91]
	v_mfma_f32_16x16x32_bf16 v[76:79], v[136:139], v[236:239], v[76:79]
	v_mfma_f32_16x16x32_bf16 v[72:75], v[144:147], v[236:239], v[72:75]
	v_mfma_f32_16x16x32_bf16 v[116:119], v[148:151], v[164:167], v[116:119]
	v_mfma_f32_16x16x32_bf16 v[112:115], v[156:159], v[164:167], v[112:115]
	v_mfma_f32_16x16x32_bf16 v[100:103], v[148:151], v[172:175], v[100:103]
	v_mfma_f32_16x16x32_bf16 v[96:99], v[156:159], v[172:175], v[96:99]
	v_mfma_f32_16x16x32_bf16 v[84:87], v[148:151], v[180:183], v[84:87]
	v_mfma_f32_16x16x32_bf16 v[80:83], v[156:159], v[180:183], v[80:83]
	v_mfma_f32_16x16x32_bf16 v[68:71], v[148:151], v[232:235], v[68:71]
	v_mfma_f32_16x16x32_bf16 v[64:67], v[156:159], v[232:235], v[64:67]
	v_mfma_f32_16x16x32_bf16 v[116:119], v[152:155], v[168:171], v[116:119]
	v_mfma_f32_16x16x32_bf16 v[112:115], v[160:163], v[168:171], v[112:115]
	v_mfma_f32_16x16x32_bf16 v[100:103], v[152:155], v[176:179], v[100:103]
	v_mfma_f32_16x16x32_bf16 v[96:99], v[160:163], v[176:179], v[96:99]
	v_mfma_f32_16x16x32_bf16 v[84:87], v[152:155], v[228:231], v[84:87]
	v_mfma_f32_16x16x32_bf16 v[80:83], v[160:163], v[228:231], v[80:83]
	v_mfma_f32_16x16x32_bf16 v[68:71], v[152:155], v[236:239], v[68:71]
	v_mfma_f32_16x16x32_bf16 v[64:67], v[160:163], v[236:239], v[64:67]
	s_barrier
	v_readfirstlane_b32 s31, v219
	v_lshl_add_u64 v[204:205], v[204:205], 0, s[2:3]
	s_mov_b32 m0, s31
	v_readfirstlane_b32 s31, v220
	s_add_u32 s8, s8, 0xb0080
	ds_read_b128 v[164:167], v226 offset:49152
	ds_read_b128 v[168:171], v226 offset:50176
	ds_read_b128 v[172:175], v226 offset:51200
	ds_read_b128 v[176:179], v226 offset:52224
	ds_read_b128 v[180:183], v226 offset:53248
	ds_read_b128 v[228:231], v226 offset:54272
	ds_read_b128 v[232:235], v226 offset:55296
	ds_read_b128 v[236:239], v226 offset:56320
	global_load_lds_dwordx4 v[204:205], off
	v_lshl_add_u64 v[204:205], v[240:241], 0, s[2:3]
	s_mov_b32 m0, s31
	s_addc_u32 s9, s9, 0
	v_readfirstlane_b32 s31, v223
	global_load_lds_dwordx4 v[204:205], off
	v_lshl_add_u64 v[204:205], s[8:9], 0, v[196:197]
	s_mov_b32 m0, s31
	s_nop 0
	global_load_lds_dwordx4 v[204:205], off
	v_lshl_add_u64 v[204:205], s[8:9], 0, v[198:199]
	v_readfirstlane_b32 s8, v224
	s_mov_b32 m0, s8
	v_readfirstlane_b32 s8, v221
	global_load_lds_dwordx4 v[204:205], off
	v_lshl_add_u64 v[204:205], v[242:243], 0, s[2:3]
	s_mov_b32 m0, s8
	v_readfirstlane_b32 s8, v222
	global_load_lds_dwordx4 v[204:205], off
	v_lshl_add_u64 v[204:205], v[244:245], 0, s[2:3]
	s_mov_b32 m0, s8
	s_nop 0
	global_load_lds_dwordx4 v[204:205], off
	s_waitcnt vmcnt(8)
	s_waitcnt lgkmcnt(0)
	s_barrier
	s_waitcnt lgkmcnt(0)
	v_mfma_f32_16x16x32_bf16 v[60:63], v[132:135], v[164:167], v[60:63]
	v_mfma_f32_16x16x32_bf16 v[56:59], v[140:143], v[164:167], v[56:59]
	v_mfma_f32_16x16x32_bf16 v[44:47], v[132:135], v[172:175], v[44:47]
	v_mfma_f32_16x16x32_bf16 v[40:43], v[140:143], v[172:175], v[40:43]
	v_mfma_f32_16x16x32_bf16 v[28:31], v[132:135], v[180:183], v[28:31]
	v_mfma_f32_16x16x32_bf16 v[24:27], v[140:143], v[180:183], v[24:27]
	v_mfma_f32_16x16x32_bf16 v[12:15], v[132:135], v[232:235], v[12:15]
	v_mfma_f32_16x16x32_bf16 v[8:11], v[140:143], v[232:235], v[8:11]
	v_mfma_f32_16x16x32_bf16 v[60:63], v[136:139], v[168:171], v[60:63]
	v_mfma_f32_16x16x32_bf16 v[56:59], v[144:147], v[168:171], v[56:59]
	v_mfma_f32_16x16x32_bf16 v[44:47], v[136:139], v[176:179], v[44:47]
	v_mfma_f32_16x16x32_bf16 v[40:43], v[144:147], v[176:179], v[40:43]
	v_mfma_f32_16x16x32_bf16 v[28:31], v[136:139], v[228:231], v[28:31]
	v_mfma_f32_16x16x32_bf16 v[24:27], v[144:147], v[228:231], v[24:27]
	v_mfma_f32_16x16x32_bf16 v[12:15], v[136:139], v[236:239], v[12:15]
	v_mfma_f32_16x16x32_bf16 v[8:11], v[144:147], v[236:239], v[8:11]
	v_mfma_f32_16x16x32_bf16 v[52:55], v[148:151], v[164:167], v[52:55]
	v_mfma_f32_16x16x32_bf16 v[48:51], v[156:159], v[164:167], v[48:51]
	v_mfma_f32_16x16x32_bf16 v[36:39], v[148:151], v[172:175], v[36:39]
	v_mfma_f32_16x16x32_bf16 v[32:35], v[156:159], v[172:175], v[32:35]
	v_mfma_f32_16x16x32_bf16 v[20:23], v[148:151], v[180:183], v[20:23]
	v_mfma_f32_16x16x32_bf16 v[16:19], v[156:159], v[180:183], v[16:19]
	v_mfma_f32_16x16x32_bf16 v[4:7], v[148:151], v[232:235], v[4:7]
	v_mfma_f32_16x16x32_bf16 v[0:3], v[156:159], v[232:235], v[0:3]
	v_mfma_f32_16x16x32_bf16 v[52:55], v[152:155], v[168:171], v[52:55]
	v_mfma_f32_16x16x32_bf16 v[48:51], v[160:163], v[168:171], v[48:51]
	v_mfma_f32_16x16x32_bf16 v[36:39], v[152:155], v[176:179], v[36:39]
	v_mfma_f32_16x16x32_bf16 v[32:35], v[160:163], v[176:179], v[32:35]
	v_mfma_f32_16x16x32_bf16 v[20:23], v[152:155], v[228:231], v[20:23]
	v_mfma_f32_16x16x32_bf16 v[16:19], v[160:163], v[228:231], v[16:19]
	v_mfma_f32_16x16x32_bf16 v[4:7], v[152:155], v[236:239], v[4:7]
	v_mfma_f32_16x16x32_bf16 v[0:3], v[160:163], v[236:239], v[0:3]
	s_barrier
	s_add_i32 s77, s77, 2
	s_add_u32 s0, s0, 0x100
	s_addc_u32 s1, s1, 0
	s_cmp_gt_u32 s77, 41
	s_cbranch_scc0 .LBB0_1441
	s_setprio 0
	s_and_saveexec_b64 s[0:1], s[40:41]
	s_cbranch_execz .LBB0_1444
	s_barrier
